# mixer work (attention units, conv_mix, pool_mix) remapped group-locally; seams 3 and 10 become local barriers, with WAR dependency tables at seams 4 and 11
# baseline (speedup 1.0000x reference)
.LBB0_266:
	s_and_b64 vcc, exec, s[12:13]
	s_cbranch_vccz .LBB0_293
	v_readlane_b32 s10, v253, 7
	v_mov_b32_e32 v76, v241
	v_readlane_b32 s11, v253, 8
	s_and_b64 vcc, exec, s[10:11]
	v_readfirstlane_b32 s6, v76
	s_cbranch_vccz .LBB0_270
	s_and_b64 s[8:9], s[8:9], exec
	s_movk_i32 s8, 0x700
	s_cselect_b32 s10, s8, 0x400
	s_movk_i32 s8, 0xc00
	s_cselect_b32 s8, s8, 0x600
	s_add_u32 s8, s72, s8
	v_readlane_b32 s12, v254, 58
	s_addc_u32 s9, s73, 0
	v_readlane_b32 s13, v254, 59
	s_and_b64 s[12:13], s[12:13], exec
	s_cselect_b32 s11, 0x80000, 0
	v_readlane_b32 s12, v252, 53
	s_add_u32 s12, s12, s11
	v_readlane_b32 s13, v252, 54
	s_addc_u32 s13, s13, 0
	v_readlane_b32 s14, v252, 55
	s_add_u32 s14, s14, s11
	v_readlane_b32 s11, v252, 56
	v_lshlrev_b32_e32 v2, 4, v76
	s_addc_u32 s15, s11, 0
	v_and_b32_e32 v0, 0x70, v2
	v_mov_b32_e32 v1, v185
	v_lshl_add_u64 v[64:65], s[14:15], 0, v[0:1]
	v_add_u32_e32 v1, 0x200, v76
	v_ashrrev_i32_e32 v79, 3, v1
	v_ashrrev_i32_e32 v80, 5, v1
	v_add_u32_e32 v1, 0x400, v76
	v_ashrrev_i32_e32 v81, 3, v1
	v_ashrrev_i32_e32 v82, 5, v1
	v_add_u32_e32 v1, 0x600, v76
	v_and_b32_e32 v15, 64, v243
	v_ashrrev_i32_e32 v83, 3, v1
	v_ashrrev_i32_e32 v84, 5, v1
	v_add_u32_e32 v1, 0, v0
	v_xor_b32_e32 v0, 16, v243
	v_add_u32_e32 v15, 64, v15
	v_cmp_lt_i32_e32 vcc, v0, v15
	s_ashr_i32 s6, s6, 1
	v_and_b32_e32 v4, 63, v76
	v_cndmask_b32_e32 v0, v243, v0, vcc
	v_lshlrev_b32_e32 v85, 2, v0
	v_xor_b32_e32 v0, 32, v243
	v_and_b32_e32 v5, 15, v76
	s_andn2_b32 s6, s6, 31
	v_and_b32_e32 v184, 48, v76
	v_cmp_lt_i32_e32 vcc, v0, v15
	v_bfe_u32 v6, v76, 4, 2
	s_ashr_i32 s11, s6, 31
	v_or_b32_e32 v60, s6, v5
	v_lshl_add_u64 v[62:63], s[8:9], 0, v[184:185]
	v_and_b32_e32 v2, 0x1f0, v2
	v_mov_b32_e32 v3, v185
	v_ashrrev_i32_e32 v77, 3, v76
	v_ashrrev_i32_e32 v78, 5, v76
	s_movk_i32 s6, 0x90
	s_movk_i32 s8, 0x210
	v_cndmask_b32_e32 v0, v243, v0, vcc
	v_or_b32_e32 v16, 48, v4
	v_or_b32_e32 v18, 0x70, v4
	v_or_b32_e32 v19, 0xb0, v4
	v_or_b32_e32 v4, 0xf0, v4
	v_lshl_add_u64 v[66:67], s[12:13], 0, v[2:3]
	v_add_u32_e32 v2, 0, v2
	v_mul_lo_u32 v3, v77, s6
	v_mul_lo_u32 v7, v78, s8
	v_mul_lo_u32 v8, v79, s6
	v_mul_lo_u32 v9, v80, s8
	v_mul_lo_u32 v10, v81, s6
	v_mul_lo_u32 v11, v82, s8
	v_mul_lo_u32 v12, v83, s6
	v_mul_lo_u32 v13, v84, s8
	v_add_u32_e32 v14, 0, v184
	v_lshlrev_b32_e32 v86, 2, v0
	v_lshl_add_u32 v15, v6, 3, 0
	v_lshlrev_b32_e32 v0, 2, v6
	v_mul_u32_u24_e32 v6, 0x90, v5
	v_mul_u32_u24_e32 v17, 0x90, v16
	v_mul_u32_u24_e32 v18, 0x90, v18
	v_mul_u32_u24_e32 v19, 0x90, v19
	v_mul_u32_u24_e32 v4, 0x90, v4
	v_mul_u32_u24_e32 v5, 0x210, v5
	v_mul_u32_u24_e32 v16, 0x210, v16
	v_mov_b32_e32 v61, s11
	v_add_u32_e32 v87, v1, v3
	v_add_u32_e32 v88, v2, v7
	v_add_u32_e32 v89, v1, v8
	v_add_u32_e32 v90, v2, v9
	v_add_u32_e32 v91, v1, v10
	v_add_u32_e32 v92, v2, v11
	v_add_u32_e32 v93, v1, v12
	v_add_u32_e32 v94, v2, v13
	v_add_u32_e32 v95, v14, v6
	v_add_u32_e32 v96, v14, v17
	v_add_u32_e32 v97, v14, v18
	v_add_u32_e32 v98, v14, v19
	v_add_u32_e32 v99, v14, v4
	v_add_u32_e32 v100, v15, v5
	v_add_u32_e32 v101, v15, v16
	v_lshlrev_b32_e32 v184, 1, v0
	v_readlane_b32 s11, v252, 33
	s_mov_b32 s12, s87
	s_cmp_eq_u32 s100, 1
	s_cbranch_scc0 .Latt_nomap
	v_readlane_b32 s6, v252, 0
	s_nop 0
	s_and_b32 s8, s6, 7
	s_lshr_b32 s6, s6, 3
	s_lshr_b32 s13, s8, 1
	s_lshl_b32 s13, s13, 2
	s_lshr_b32 s14, s6, 3
	s_add_i32 s13, s13, s14
	s_lshl_b32 s13, s13, 4
	s_and_b32 s14, s8, 1
	s_lshl_b32 s14, s14, 3
	s_and_b32 s6, s6, 7
	s_add_i32 s14, s14, s6
	s_add_i32 s12, s13, s14
	s_lshl_b32 s11, s12, 9
.Latt_nomap:
.LBB0_269:
	s_ashr_i32 s6, s12, 31
	s_lshr_b32 s6, s6, 28
	s_add_i32 s6, s12, s6
	s_ashr_i32 s13, s6, 4
	s_ashr_i32 s8, s6, 6
	s_lshl_b32 s6, s13, 13
	s_ashr_i32 s9, s8, 31
	s_sub_i32 s14, s11, s6
	s_lshl_b64 s[16:17], s[8:9], 13
	v_lshl_add_u64 v[0:1], v[60:61], 0, s[16:17]
	s_ashr_i32 s15, s14, 31
	v_lshl_add_u64 v[74:75], v[0:1], 0, s[14:15]
	s_lshl_b32 s6, s13, 6
	v_mad_u64_u32 v[4:5], s[16:17], v74, s10, 0
	s_and_b32 s6, s6, 0xc0
	v_mov_b32_e32 v6, v5
	s_lshl_b32 s70, s6, 1
	v_mad_u64_u32 v[6:7], s[16:17], v75, s10, v[6:7]
	v_lshl_add_u64 v[2:3], v[62:63], 0, s[70:71]
	v_mov_b32_e32 v5, v6
	v_lshl_add_u64 v[4:5], v[4:5], 1, v[2:3]
	global_load_dwordx4 v[24:27], v[4:5], off
	global_load_dwordx4 v[28:31], v[4:5], off offset:64
	v_or_b32_e32 v4, 16, v0
	v_mov_b32_e32 v5, v1
	v_lshl_add_u64 v[72:73], v[4:5], 0, s[14:15]
	v_mad_u64_u32 v[6:7], s[16:17], v72, s10, 0
	v_mov_b32_e32 v8, v7
	s_addk_i32 s14, 0x100
	v_mad_u64_u32 v[8:9], s[16:17], v73, s10, v[8:9]
	s_ashr_i32 s15, s14, 31
	v_mov_b32_e32 v7, v8
	v_lshl_add_u64 v[70:71], v[0:1], 0, s[14:15]
	v_lshl_add_u64 v[6:7], v[6:7], 1, v[2:3]
	v_mad_u64_u32 v[0:1], s[16:17], v70, s10, 0
	global_load_dwordx4 v[16:19], v[6:7], off
	global_load_dwordx4 v[20:23], v[6:7], off offset:64
	v_mov_b32_e32 v6, v1
	v_mad_u64_u32 v[6:7], s[16:17], v71, s10, v[6:7]
	v_mov_b32_e32 v1, v6
	v_lshl_add_u64 v[0:1], v[0:1], 1, v[2:3]
	v_lshl_add_u64 v[68:69], v[4:5], 0, s[14:15]
	global_load_dwordx4 v[8:11], v[0:1], off
	global_load_dwordx4 v[12:15], v[0:1], off offset:64
	v_mad_u64_u32 v[0:1], s[14:15], v68, s10, 0
	s_lshl_b32 s8, s8, 8
	v_mov_b32_e32 v4, v1
	v_add_u32_e32 v32, s8, v77
	v_mad_u64_u32 v[4:5], s[14:15], v69, s10, v[4:5]
	v_ashrrev_i32_e32 v33, 31, v32
	v_add_u32_e32 v36, s6, v78
	v_mov_b32_e32 v1, v4
	v_lshl_add_u64 v[56:57], v[64:65], 0, s[70:71]
	s_ashr_i32 s9, s8, 31
	v_lshlrev_b64 v[32:33], 9, v[32:33]
	v_ashrrev_i32_e32 v37, 31, v36
	v_add_u32_e32 v40, s8, v79
	v_lshl_add_u64 v[4:5], v[0:1], 1, v[2:3]
	v_lshl_add_u64 v[102:103], s[8:9], 1, v[66:67]
	v_lshl_add_u64 v[32:33], v[56:57], 0, v[32:33]
	v_lshlrev_b64 v[36:37], 11, v[36:37]
	v_ashrrev_i32_e32 v41, 31, v40
	v_add_u32_e32 v44, s6, v80
	global_load_dwordx4 v[0:3], v[4:5], off
	s_nop 0
	global_load_dwordx4 v[4:7], v[4:5], off offset:64
	v_lshl_add_u64 v[36:37], v[102:103], 0, v[36:37]
	global_load_dwordx4 v[32:35], v[32:33], off
	v_lshlrev_b64 v[40:41], 9, v[40:41]
	v_ashrrev_i32_e32 v45, 31, v44
	v_add_u32_e32 v48, s8, v81
	global_load_dwordx4 v[36:39], v[36:37], off
	v_lshl_add_u64 v[40:41], v[56:57], 0, v[40:41]
	v_lshlrev_b64 v[44:45], 11, v[44:45]
	v_ashrrev_i32_e32 v49, 31, v48
	v_add_u32_e32 v52, s6, v82
	global_load_dwordx4 v[40:43], v[40:41], off
	v_lshl_add_u64 v[44:45], v[102:103], 0, v[44:45]
	v_lshlrev_b64 v[48:49], 9, v[48:49]
	v_ashrrev_i32_e32 v53, 31, v52
	v_add_u32_e32 v58, s8, v83
	global_load_dwordx4 v[44:47], v[44:45], off
	v_lshl_add_u64 v[48:49], v[56:57], 0, v[48:49]
	v_lshlrev_b64 v[52:53], 11, v[52:53]
	v_ashrrev_i32_e32 v59, 31, v58
	v_add_u32_e32 v104, s6, v84
	global_load_dwordx4 v[48:51], v[48:49], off
	v_lshl_add_u64 v[52:53], v[102:103], 0, v[52:53]
	v_lshlrev_b64 v[58:59], 9, v[58:59]
	v_ashrrev_i32_e32 v105, 31, v104
	global_load_dwordx4 v[52:55], v[52:53], off
	v_lshl_add_u64 v[56:57], v[56:57], 0, v[58:59]
	v_lshlrev_b64 v[104:105], 11, v[104:105]
	global_load_dwordx4 v[56:59], v[56:57], off
	v_lshl_add_u64 v[102:103], v[102:103], 0, v[104:105]
	global_load_dwordx4 v[102:105], v[102:103], off
	s_add_i32 s12, s12, s20
	s_add_i32 s11, s11, s76
	s_cmpk_gt_i32 s12, 0xff
	s_waitcnt vmcnt(0)
	ds_write_b128 v87, v[32:35]
	ds_write_b128 v88, v[36:39] offset:36864
	ds_write_b128 v89, v[40:43]
	ds_write_b128 v90, v[44:47] offset:36864
	ds_write_b128 v91, v[48:51]
	ds_write_b128 v92, v[52:55] offset:36864
	ds_write_b128 v93, v[56:59]
	ds_write_b128 v94, v[102:105] offset:36864
	s_waitcnt lgkmcnt(0)
	s_barrier
	ds_read_b128 v[32:35], v95
	ds_read_b128 v[36:39], v95 offset:64
	s_waitcnt lgkmcnt(1)
	v_mfma_f32_16x16x32_bf16 v[32:35], v[32:35], v[24:27], 0
	s_waitcnt lgkmcnt(0)
	v_mfma_f32_16x16x32_bf16 v[102:105], v[36:39], v[28:31], v[32:35]
	s_nop 5
	ds_read_b128 v[32:35], v95 offset:2304
	ds_read_b128 v[36:39], v95 offset:2368
	s_waitcnt lgkmcnt(1)
	v_mfma_f32_16x16x32_bf16 v[32:35], v[32:35], v[24:27], 0
	s_waitcnt lgkmcnt(0)
	v_mfma_f32_16x16x32_bf16 v[106:109], v[36:39], v[28:31], v[32:35]
	s_nop 5
	ds_read_b128 v[32:35], v95 offset:4608
	ds_read_b128 v[36:39], v95 offset:4672
	s_waitcnt lgkmcnt(1)
	v_mfma_f32_16x16x32_bf16 v[32:35], v[32:35], v[24:27], 0
	s_waitcnt lgkmcnt(0)
	v_mfma_f32_16x16x32_bf16 v[110:113], v[36:39], v[28:31], v[32:35]
	s_nop 5
	ds_read_b128 v[32:35], v96
	ds_read_b128 v[36:39], v96 offset:64
	s_waitcnt lgkmcnt(1)
	v_mfma_f32_16x16x32_bf16 v[32:35], v[32:35], v[24:27], 0
	s_waitcnt lgkmcnt(0)
	v_mfma_f32_16x16x32_bf16 v[114:117], v[36:39], v[28:31], v[32:35]
	s_nop 5
	ds_read_b128 v[32:35], v95 offset:9216
	ds_read_b128 v[36:39], v95 offset:9280
	s_waitcnt lgkmcnt(1)
	v_mfma_f32_16x16x32_bf16 v[32:35], v[32:35], v[24:27], 0
	s_waitcnt lgkmcnt(0)
	v_mfma_f32_16x16x32_bf16 v[118:121], v[36:39], v[28:31], v[32:35]
	s_nop 5
	ds_read_b128 v[32:35], v95 offset:11520
	ds_read_b128 v[36:39], v95 offset:11584
	s_waitcnt lgkmcnt(1)
	v_mfma_f32_16x16x32_bf16 v[32:35], v[32:35], v[24:27], 0
	s_waitcnt lgkmcnt(0)
	v_mfma_f32_16x16x32_bf16 v[122:125], v[36:39], v[28:31], v[32:35]
	s_nop 5
	ds_read_b128 v[32:35], v95 offset:13824
	ds_read_b128 v[36:39], v95 offset:13888
	s_waitcnt lgkmcnt(1)
	v_mfma_f32_16x16x32_bf16 v[32:35], v[32:35], v[24:27], 0
	s_waitcnt lgkmcnt(0)
	v_mfma_f32_16x16x32_bf16 v[126:129], v[36:39], v[28:31], v[32:35]
	s_nop 5
	ds_read_b128 v[32:35], v97
	ds_read_b128 v[36:39], v97 offset:64
	s_waitcnt lgkmcnt(1)
	v_mfma_f32_16x16x32_bf16 v[32:35], v[32:35], v[24:27], 0
	s_waitcnt lgkmcnt(0)
	v_mfma_f32_16x16x32_bf16 v[130:133], v[36:39], v[28:31], v[32:35]
	s_nop 5
	ds_read_b128 v[32:35], v95 offset:18432
	ds_read_b128 v[36:39], v95 offset:18496
	s_waitcnt lgkmcnt(1)
	v_mfma_f32_16x16x32_bf16 v[32:35], v[32:35], v[24:27], 0
	s_waitcnt lgkmcnt(0)
	v_mfma_f32_16x16x32_bf16 v[56:59], v[36:39], v[28:31], v[32:35]
	s_nop 5
	ds_read_b128 v[32:35], v95 offset:20736
	ds_read_b128 v[36:39], v95 offset:20800
	s_waitcnt lgkmcnt(1)
	v_mfma_f32_16x16x32_bf16 v[32:35], v[32:35], v[24:27], 0
	s_waitcnt lgkmcnt(0)
	v_mfma_f32_16x16x32_bf16 v[52:55], v[36:39], v[28:31], v[32:35]
	s_nop 5
	ds_read_b128 v[32:35], v95 offset:23040
	ds_read_b128 v[36:39], v95 offset:23104
	s_waitcnt lgkmcnt(1)
	v_mfma_f32_16x16x32_bf16 v[32:35], v[32:35], v[24:27], 0
	s_waitcnt lgkmcnt(0)
	v_mfma_f32_16x16x32_bf16 v[48:51], v[36:39], v[28:31], v[32:35]
	s_nop 5
	ds_read_b128 v[32:35], v98
	ds_read_b128 v[36:39], v98 offset:64
	s_waitcnt lgkmcnt(1)
	v_mfma_f32_16x16x32_bf16 v[32:35], v[32:35], v[24:27], 0
	s_waitcnt lgkmcnt(0)
	v_mfma_f32_16x16x32_bf16 v[44:47], v[36:39], v[28:31], v[32:35]
	s_nop 5
	ds_read_b128 v[32:35], v95 offset:27648
	ds_read_b128 v[36:39], v95 offset:27712
	s_waitcnt lgkmcnt(1)
	v_mfma_f32_16x16x32_bf16 v[32:35], v[32:35], v[24:27], 0
	s_waitcnt lgkmcnt(0)
	v_mfma_f32_16x16x32_bf16 v[40:43], v[36:39], v[28:31], v[32:35]
	s_nop 5
	ds_read_b128 v[32:35], v95 offset:29952
	ds_read_b128 v[36:39], v95 offset:30016
	s_waitcnt lgkmcnt(1)
	v_mfma_f32_16x16x32_bf16 v[32:35], v[32:35], v[24:27], 0
	s_waitcnt lgkmcnt(0)
	v_mfma_f32_16x16x32_bf16 v[36:39], v[36:39], v[28:31], v[32:35]
	s_nop 5
	ds_read_b128 v[32:35], v95 offset:32256
	ds_read_b128 v[134:137], v95 offset:32320
	s_waitcnt lgkmcnt(1)
	v_mfma_f32_16x16x32_bf16 v[32:35], v[32:35], v[24:27], 0
	s_waitcnt lgkmcnt(0)
	v_mfma_f32_16x16x32_bf16 v[32:35], v[134:137], v[28:31], v[32:35]
	ds_read_b128 v[134:137], v99
	ds_read_b128 v[138:141], v99 offset:64
	s_waitcnt lgkmcnt(1)
	v_mfma_f32_16x16x32_bf16 v[24:27], v[134:137], v[24:27], 0
	s_waitcnt lgkmcnt(0)
	v_mfma_f32_16x16x32_bf16 v[24:27], v[138:141], v[28:31], v[24:27]
	v_max3_f32 v28, v102, v103, v104
	v_max_f32_e32 v29, v108, v108
	v_max_f32_e32 v30, v107, v107
	v_max3_f32 v28, v28, v105, v106
	v_max_f32_e32 v29, v30, v29
	v_max3_f32 v28, v28, v29, v109
	v_max_f32_e32 v29, v112, v112
	v_max_f32_e32 v30, v111, v111
	v_max_f32_e32 v29, v30, v29
	v_max3_f32 v28, v28, v110, v29
	v_max_f32_e32 v29, v116, v116
	v_max_f32_e32 v30, v115, v115
	v_max3_f32 v28, v28, v113, v114
	v_max_f32_e32 v29, v30, v29
	v_max3_f32 v28, v28, v29, v117
	v_max_f32_e32 v29, v120, v120
	v_max_f32_e32 v30, v119, v119
	v_max_f32_e32 v29, v30, v29
	v_max3_f32 v28, v28, v118, v29
	v_max_f32_e32 v29, v124, v124
	v_max_f32_e32 v30, v123, v123
	v_max3_f32 v28, v28, v121, v122
	v_max_f32_e32 v29, v30, v29
	v_max3_f32 v28, v28, v29, v125
	v_max_f32_e32 v29, v128, v128
	v_max_f32_e32 v30, v127, v127
	v_max_f32_e32 v29, v30, v29
	v_max3_f32 v28, v28, v126, v29
	v_max_f32_e32 v29, v132, v132
	v_max_f32_e32 v30, v131, v131
	v_max3_f32 v28, v28, v129, v130
	v_max_f32_e32 v29, v30, v29
	v_max3_f32 v28, v28, v29, v133
	v_max_f32_e32 v29, v58, v58
	v_max_f32_e32 v30, v57, v57
	v_max_f32_e32 v29, v30, v29
	v_max3_f32 v28, v28, v56, v29
	v_max_f32_e32 v29, v54, v54
	v_max_f32_e32 v30, v53, v53
	v_max3_f32 v28, v28, v59, v52
	v_max_f32_e32 v29, v30, v29
	v_max3_f32 v28, v28, v29, v55
	v_max_f32_e32 v29, v50, v50
	v_max_f32_e32 v30, v49, v49
	v_max_f32_e32 v29, v30, v29
	v_max3_f32 v28, v28, v48, v29
	v_max_f32_e32 v29, v46, v46
	v_max_f32_e32 v30, v45, v45
	v_max3_f32 v28, v28, v51, v44
	v_max_f32_e32 v29, v30, v29
	v_max3_f32 v28, v28, v29, v47
	v_max_f32_e32 v29, v42, v42
	v_max_f32_e32 v30, v41, v41
	v_max_f32_e32 v29, v30, v29
	v_max3_f32 v28, v28, v40, v29
	v_max_f32_e32 v29, v38, v38
	v_max_f32_e32 v30, v37, v37
	v_max3_f32 v28, v28, v43, v36
	v_max_f32_e32 v29, v30, v29
	v_max3_f32 v28, v28, v29, v39
	v_max_f32_e32 v29, v34, v34
	v_max_f32_e32 v30, v33, v33
	v_max_f32_e32 v29, v30, v29
	v_max3_f32 v28, v28, v32, v29
	v_max_f32_e32 v29, v26, v26
	v_max_f32_e32 v30, v25, v25
	v_max3_f32 v28, v28, v35, v24
	v_max_f32_e32 v29, v30, v29
	v_max3_f32 v28, v28, v29, v27
	ds_bpermute_b32 v29, v85, v28
	s_waitcnt lgkmcnt(0)
	v_max_f32_e32 v29, v29, v29
	v_max_f32_e32 v28, v28, v29
	ds_bpermute_b32 v29, v86, v28
	s_waitcnt lgkmcnt(0)
	v_max_f32_e32 v29, v29, v29
	v_max_f32_e32 v134, v28, v29
	v_sub_f32_e32 v29, v103, v134
	v_mul_f32_e32 v29, 0x3e38aa3b, v29
	v_exp_f32_e32 v136, v29
	v_sub_f32_e32 v29, v104, v134
	v_mul_f32_e32 v29, 0x3e38aa3b, v29
	v_exp_f32_e32 v137, v29
	v_sub_f32_e32 v29, v105, v134
	v_sub_f32_e32 v28, v102, v134
	v_mul_f32_e32 v29, 0x3e38aa3b, v29
	v_mul_f32_e32 v28, 0x3e38aa3b, v28
	v_exp_f32_e32 v138, v29
	v_sub_f32_e32 v29, v106, v134
	v_exp_f32_e32 v135, v28
	v_mul_f32_e32 v29, 0x3e38aa3b, v29
	v_exp_f32_e32 v139, v29
	v_sub_f32_e32 v29, v107, v134
	v_mul_f32_e32 v29, 0x3e38aa3b, v29
	v_exp_f32_e32 v140, v29
	v_sub_f32_e32 v29, v108, v134
	v_add_f32_e32 v28, 0, v135
	v_mul_f32_e32 v29, 0x3e38aa3b, v29
	v_add_f32_e32 v28, v136, v28
	v_exp_f32_e32 v141, v29
	v_sub_f32_e32 v29, v109, v134
	v_add_f32_e32 v28, v137, v28
	v_mul_f32_e32 v29, 0x3e38aa3b, v29
	v_add_f32_e32 v28, v138, v28
	v_exp_f32_e32 v142, v29
	v_add_f32_e32 v28, v139, v28
	v_add_f32_e32 v28, v140, v28
	v_add_f32_e32 v28, v141, v28
	v_add_f32_e32 v29, v142, v28
	v_sub_f32_e32 v28, v110, v134
	v_mul_f32_e32 v28, 0x3e38aa3b, v28
	v_exp_f32_e32 v28, v28
	v_sub_f32_e32 v105, v116, v134
	v_mul_f32_e32 v105, 0x3e38aa3b, v105
	v_sub_f32_e32 v106, v117, v134
	v_add_f32_e32 v30, v28, v29
	v_sub_f32_e32 v29, v111, v134
	v_mul_f32_e32 v29, 0x3e38aa3b, v29
	v_exp_f32_e32 v29, v29
	v_exp_f32_e32 v105, v105
	v_mul_f32_e32 v106, 0x3e38aa3b, v106
	v_exp_f32_e32 v107, v106
	v_add_f32_e32 v31, v29, v30
	v_sub_f32_e32 v30, v112, v134
	v_mul_f32_e32 v30, 0x3e38aa3b, v30
	v_exp_f32_e32 v30, v30
	v_sub_f32_e32 v56, v56, v134
	v_mul_f32_e32 v56, 0x3e38aa3b, v56
	v_sub_f32_e32 v57, v57, v134
	v_add_f32_e32 v102, v30, v31
	v_sub_f32_e32 v31, v113, v134
	v_mul_f32_e32 v31, 0x3e38aa3b, v31
	v_exp_f32_e32 v31, v31
	v_sub_f32_e32 v113, v124, v134
	v_mul_f32_e32 v113, 0x3e38aa3b, v113
	v_exp_f32_e32 v113, v113
	v_add_f32_e32 v103, v31, v102
	v_sub_f32_e32 v102, v114, v134
	v_mul_f32_e32 v102, 0x3e38aa3b, v102
	v_exp_f32_e32 v102, v102
	v_sub_f32_e32 v114, v125, v134
	v_mul_f32_e32 v114, 0x3e38aa3b, v114
	v_exp_f32_e32 v56, v56
	v_add_f32_e32 v104, v102, v103
	v_sub_f32_e32 v103, v115, v134
	v_mul_f32_e32 v103, 0x3e38aa3b, v103
	v_exp_f32_e32 v103, v103
	v_exp_f32_e32 v115, v114
	v_mul_f32_e32 v57, 0x3e38aa3b, v57
	v_sub_f32_e32 v58, v58, v134
	v_add_f32_e32 v104, v103, v104
	v_add_f32_e32 v104, v105, v104
	v_add_f32_e32 v106, v107, v104
	v_sub_f32_e32 v104, v118, v134
	v_mul_f32_e32 v104, 0x3e38aa3b, v104
	v_exp_f32_e32 v104, v104
	v_exp_f32_e32 v57, v57
	v_mul_f32_e32 v58, 0x3e38aa3b, v58
	v_sub_f32_e32 v59, v59, v134
	v_add_f32_e32 v108, v104, v106
	v_sub_f32_e32 v106, v119, v134
	v_mul_f32_e32 v106, 0x3e38aa3b, v106
	v_exp_f32_e32 v106, v106
	v_exp_f32_e32 v58, v58
	v_mul_f32_e32 v59, 0x3e38aa3b, v59
	v_exp_f32_e32 v59, v59
	v_add_f32_e32 v109, v106, v108
	v_sub_f32_e32 v108, v120, v134
	v_mul_f32_e32 v108, 0x3e38aa3b, v108
	v_exp_f32_e32 v108, v108
	v_sub_f32_e32 v52, v52, v134
	v_mul_f32_e32 v52, 0x3e38aa3b, v52
	v_sub_f32_e32 v53, v53, v134
	v_add_f32_e32 v110, v108, v109
	v_sub_f32_e32 v109, v121, v134
	v_mul_f32_e32 v109, 0x3e38aa3b, v109
	v_exp_f32_e32 v109, v109
	v_mul_f32_e32 v53, 0x3e38aa3b, v53
	v_sub_f32_e32 v48, v48, v134
	v_mul_f32_e32 v48, 0x3e38aa3b, v48
	v_add_f32_e32 v111, v109, v110
	v_sub_f32_e32 v110, v122, v134
	v_mul_f32_e32 v110, 0x3e38aa3b, v110
	v_exp_f32_e32 v110, v110
	v_sub_f32_e32 v49, v49, v134
	v_exp_f32_e32 v48, v48
	v_mul_f32_e32 v49, 0x3e38aa3b, v49
	v_add_f32_e32 v112, v110, v111
	v_sub_f32_e32 v111, v123, v134
	v_mul_f32_e32 v111, 0x3e38aa3b, v111
	v_exp_f32_e32 v111, v111
	v_sub_f32_e32 v50, v50, v134
	v_exp_f32_e32 v49, v49
	v_mul_f32_e32 v50, 0x3e38aa3b, v50
	v_add_f32_e32 v112, v111, v112
	v_add_f32_e32 v112, v113, v112
	v_add_f32_e32 v114, v115, v112
	v_sub_f32_e32 v112, v126, v134
	v_mul_f32_e32 v112, 0x3e38aa3b, v112
	v_exp_f32_e32 v112, v112
	v_sub_f32_e32 v51, v51, v134
	v_exp_f32_e32 v50, v50
	v_mul_f32_e32 v51, 0x3e38aa3b, v51
	v_add_f32_e32 v116, v112, v114
	v_sub_f32_e32 v114, v127, v134
	v_mul_f32_e32 v114, 0x3e38aa3b, v114
	v_exp_f32_e32 v114, v114
	v_sub_f32_e32 v44, v44, v134
	v_exp_f32_e32 v51, v51
	v_mul_f32_e32 v44, 0x3e38aa3b, v44
	v_add_f32_e32 v117, v114, v116
	v_sub_f32_e32 v116, v128, v134
	v_mul_f32_e32 v116, 0x3e38aa3b, v116
	v_exp_f32_e32 v116, v116
	v_sub_f32_e32 v45, v45, v134
	v_exp_f32_e32 v44, v44
	v_mul_f32_e32 v45, 0x3e38aa3b, v45
	v_add_f32_e32 v118, v116, v117
	v_sub_f32_e32 v117, v129, v134
	v_mul_f32_e32 v117, 0x3e38aa3b, v117
	v_exp_f32_e32 v117, v117
	v_sub_f32_e32 v46, v46, v134
	v_exp_f32_e32 v45, v45
	v_mul_f32_e32 v46, 0x3e38aa3b, v46
	v_add_f32_e32 v119, v117, v118
	v_sub_f32_e32 v118, v130, v134
	v_mul_f32_e32 v118, 0x3e38aa3b, v118
	v_exp_f32_e32 v118, v118
	v_sub_f32_e32 v47, v47, v134
	v_exp_f32_e32 v46, v46
	v_mul_f32_e32 v47, 0x3e38aa3b, v47
	v_add_f32_e32 v120, v118, v119
	v_sub_f32_e32 v119, v131, v134
	v_mul_f32_e32 v119, 0x3e38aa3b, v119
	v_exp_f32_e32 v119, v119
	v_sub_f32_e32 v40, v40, v134
	v_exp_f32_e32 v47, v47
	v_mul_f32_e32 v40, 0x3e38aa3b, v40
	v_add_f32_e32 v121, v119, v120
	v_sub_f32_e32 v120, v132, v134
	v_mul_f32_e32 v120, 0x3e38aa3b, v120
	v_exp_f32_e32 v120, v120
	v_sub_f32_e32 v41, v41, v134
	v_exp_f32_e32 v40, v40
	v_mul_f32_e32 v41, 0x3e38aa3b, v41
	v_add_f32_e32 v122, v120, v121
	v_sub_f32_e32 v121, v133, v134
	v_mul_f32_e32 v121, 0x3e38aa3b, v121
	v_exp_f32_e32 v121, v121
	v_sub_f32_e32 v42, v42, v134
	v_exp_f32_e32 v41, v41
	v_mul_f32_e32 v42, 0x3e38aa3b, v42
	v_add_f32_e32 v122, v121, v122
	v_add_f32_e32 v122, v56, v122
	v_add_f32_e32 v122, v57, v122
	v_add_f32_e32 v122, v58, v122
	v_add_f32_e32 v123, v59, v122
	v_exp_f32_e32 v122, v52
	v_sub_f32_e32 v43, v43, v134
	v_exp_f32_e32 v42, v42
	v_mul_f32_e32 v43, 0x3e38aa3b, v43
	v_add_f32_e32 v52, v122, v123
	v_exp_f32_e32 v123, v53
	v_sub_f32_e32 v53, v54, v134
	v_mul_f32_e32 v53, 0x3e38aa3b, v53
	v_exp_f32_e32 v124, v53
	v_sub_f32_e32 v53, v55, v134
	v_mul_f32_e32 v53, 0x3e38aa3b, v53
	v_exp_f32_e32 v125, v53
	v_add_f32_e32 v52, v123, v52
	v_add_f32_e32 v52, v124, v52
	v_sub_f32_e32 v36, v36, v134
	v_add_f32_e32 v52, v125, v52
	v_add_f32_e32 v52, v48, v52
	v_add_f32_e32 v52, v49, v52
	v_add_f32_e32 v52, v50, v52
	v_add_f32_e32 v52, v51, v52
	v_add_f32_e32 v52, v44, v52
	v_add_f32_e32 v52, v45, v52
	v_add_f32_e32 v52, v46, v52
	v_add_f32_e32 v52, v47, v52
	v_exp_f32_e32 v43, v43
	v_mul_f32_e32 v36, 0x3e38aa3b, v36
	v_sub_f32_e32 v37, v37, v134
	v_add_f32_e32 v52, v40, v52
	v_exp_f32_e32 v36, v36
	v_mul_f32_e32 v37, 0x3e38aa3b, v37
	v_sub_f32_e32 v38, v38, v134
	v_add_f32_e32 v52, v41, v52
	v_exp_f32_e32 v37, v37
	v_mul_f32_e32 v38, 0x3e38aa3b, v38
	v_sub_f32_e32 v39, v39, v134
	v_add_f32_e32 v52, v42, v52
	v_exp_f32_e32 v38, v38
	v_mul_f32_e32 v39, 0x3e38aa3b, v39
	v_sub_f32_e32 v32, v32, v134
	v_add_f32_e32 v52, v43, v52
	v_exp_f32_e32 v39, v39
	v_mul_f32_e32 v32, 0x3e38aa3b, v32
	v_sub_f32_e32 v33, v33, v134
	v_add_f32_e32 v52, v36, v52
	v_exp_f32_e32 v32, v32
	v_mul_f32_e32 v33, 0x3e38aa3b, v33
	v_sub_f32_e32 v34, v34, v134
	v_add_f32_e32 v52, v37, v52
	v_exp_f32_e32 v33, v33
	v_mul_f32_e32 v34, 0x3e38aa3b, v34
	v_sub_f32_e32 v35, v35, v134
	v_sub_f32_e32 v25, v25, v134
	v_add_f32_e32 v52, v38, v52
	v_exp_f32_e32 v34, v34
	v_mul_f32_e32 v35, 0x3e38aa3b, v35
	v_sub_f32_e32 v24, v24, v134
	v_mul_f32_e32 v25, 0x3e38aa3b, v25
	v_add_f32_e32 v52, v39, v52
	v_exp_f32_e32 v35, v35
	v_mul_f32_e32 v24, 0x3e38aa3b, v24
	v_exp_f32_e32 v127, v25
	v_sub_f32_e32 v25, v26, v134
	v_add_f32_e32 v52, v32, v52
	v_exp_f32_e32 v126, v24
	v_mul_f32_e32 v25, 0x3e38aa3b, v25
	v_add_f32_e32 v52, v33, v52
	v_exp_f32_e32 v130, v25
	v_sub_f32_e32 v25, v27, v134
	v_add_f32_e32 v52, v34, v52
	v_mul_f32_e32 v25, 0x3e38aa3b, v25
	v_add_f32_e32 v52, v35, v52
	v_exp_f32_e32 v131, v25
	v_add_f32_e32 v24, v126, v52
	v_add_f32_e32 v24, v127, v24
	v_add_f32_e32 v24, v130, v24
	v_add_f32_e32 v24, v131, v24
	ds_bpermute_b32 v25, v85, v24
	v_add_u32_e32 v52, 0x9000, v100
	v_add_u32_e32 v53, 0xb000, v100
	v_add_u32_e32 v54, 0xd000, v100
	v_add_u32_e32 v55, 0x9000, v101
	s_waitcnt lgkmcnt(0)
	v_add_f32_e32 v128, v24, v25
	v_cvt_pk_bf16_f32 v24, v135, v136
	v_cvt_pk_bf16_f32 v25, v137, v138
	v_cvt_pk_bf16_f32 v26, v139, v140
	v_cvt_pk_bf16_f32 v27, v141, v142
	ds_read2_b64 v[132:135], v52 offset1:4
	ds_read2_b64 v[136:139], v53 offset0:32 offset1:36
	ds_read2_b64 v[140:143], v54 offset0:64 offset1:68
	ds_read2_b64 v[144:147], v55 offset1:4
	s_waitcnt lgkmcnt(3)
	v_mfma_f32_16x16x32_bf16 v[132:135], v[132:135], v[24:27], 0
	v_cvt_pk_bf16_f32 v28, v28, v29
	v_cvt_pk_bf16_f32 v29, v30, v31
	v_cvt_pk_bf16_f32 v30, v102, v103
	s_waitcnt lgkmcnt(2)
	v_mfma_f32_16x16x32_bf16 v[136:139], v[136:139], v[24:27], 0
	v_cvt_pk_bf16_f32 v31, v105, v107
	ds_bpermute_b32 v129, v86, v128
	s_waitcnt lgkmcnt(2)
	v_mfma_f32_16x16x32_bf16 v[140:143], v[140:143], v[24:27], 0
	s_waitcnt lgkmcnt(1)
	v_mfma_f32_16x16x32_bf16 v[24:27], v[144:147], v[24:27], 0
	ds_read2_b64 v[144:147], v52 offset0:8 offset1:12
	s_waitcnt lgkmcnt(0)
	v_mfma_f32_16x16x32_bf16 v[132:135], v[144:147], v[28:31], v[132:135]
	ds_read2_b64 v[144:147], v53 offset0:40 offset1:44
	s_waitcnt lgkmcnt(0)
	v_mfma_f32_16x16x32_bf16 v[136:139], v[144:147], v[28:31], v[136:139]
	ds_read2_b64 v[144:147], v54 offset0:72 offset1:76
	s_waitcnt lgkmcnt(0)
	v_mfma_f32_16x16x32_bf16 v[140:143], v[144:147], v[28:31], v[140:143]
	ds_read2_b64 v[144:147], v55 offset0:8 offset1:12
	s_waitcnt lgkmcnt(0)
	v_mfma_f32_16x16x32_bf16 v[24:27], v[144:147], v[28:31], v[24:27]
	v_cvt_pk_bf16_f32 v28, v104, v106
	v_cvt_pk_bf16_f32 v29, v108, v109
	v_cvt_pk_bf16_f32 v30, v110, v111
	v_cvt_pk_bf16_f32 v31, v113, v115
	ds_read2_b64 v[102:105], v52 offset0:16 offset1:20
	ds_read2_b64 v[106:109], v53 offset0:48 offset1:52
	s_waitcnt lgkmcnt(1)
	v_mfma_f32_16x16x32_bf16 v[102:105], v[102:105], v[28:31], v[132:135]
	s_nop 2
	ds_read2_b64 v[132:135], v54 offset0:80 offset1:84
	s_waitcnt lgkmcnt(1)
	v_mfma_f32_16x16x32_bf16 v[106:109], v[106:109], v[28:31], v[136:139]
	s_nop 2
	ds_read2_b64 v[136:139], v55 offset0:16 offset1:20
	s_waitcnt lgkmcnt(1)
	v_mfma_f32_16x16x32_bf16 v[132:135], v[132:135], v[28:31], v[140:143]
	s_waitcnt lgkmcnt(0)
	v_mfma_f32_16x16x32_bf16 v[24:27], v[136:139], v[28:31], v[24:27]
	v_cvt_pk_bf16_f32 v28, v112, v114
	v_cvt_pk_bf16_f32 v29, v116, v117
	v_cvt_pk_bf16_f32 v30, v118, v119
	v_cvt_pk_bf16_f32 v31, v120, v121
	ds_read2_b64 v[110:113], v52 offset0:24 offset1:28
	s_waitcnt lgkmcnt(0)
	v_mfma_f32_16x16x32_bf16 v[102:105], v[110:113], v[28:31], v[102:105]
	ds_read2_b64 v[110:113], v53 offset0:56 offset1:60
	ds_read2_b64 v[114:117], v55 offset0:24 offset1:28
	s_waitcnt lgkmcnt(1)
	v_mfma_f32_16x16x32_bf16 v[106:109], v[110:113], v[28:31], v[106:109]
	ds_read2_b64 v[110:113], v54 offset0:88 offset1:92
	s_waitcnt lgkmcnt(0)
	v_mfma_f32_16x16x32_bf16 v[110:113], v[110:113], v[28:31], v[132:135]
	v_mfma_f32_16x16x32_bf16 v[24:27], v[114:117], v[28:31], v[24:27]
	v_cvt_pk_bf16_f32 v28, v56, v57
	v_cvt_pk_bf16_f32 v29, v58, v59
	v_cvt_pk_bf16_f32 v30, v122, v123
	v_cvt_pk_bf16_f32 v31, v124, v125
	ds_read2_b64 v[56:59], v52 offset0:32 offset1:36
	s_waitcnt lgkmcnt(0)
	v_mfma_f32_16x16x32_bf16 v[56:59], v[56:59], v[28:31], v[102:105]
	s_nop 2
	ds_read2_b64 v[102:105], v53 offset0:64 offset1:68
	s_waitcnt lgkmcnt(0)
	v_mfma_f32_16x16x32_bf16 v[102:105], v[102:105], v[28:31], v[106:109]
	s_nop 2
	ds_read2_b64 v[106:109], v54 offset0:96 offset1:100
	s_waitcnt lgkmcnt(0)
	v_mfma_f32_16x16x32_bf16 v[106:109], v[106:109], v[28:31], v[110:113]
	s_nop 2
	ds_read2_b64 v[110:113], v55 offset0:32 offset1:36
	s_waitcnt lgkmcnt(0)
	v_mfma_f32_16x16x32_bf16 v[24:27], v[110:113], v[28:31], v[24:27]
	v_cvt_pk_bf16_f32 v28, v48, v49
	v_cvt_pk_bf16_f32 v29, v50, v51
	v_cvt_pk_bf16_f32 v30, v44, v45
	v_cvt_pk_bf16_f32 v31, v46, v47
	ds_read2_b64 v[44:47], v52 offset0:40 offset1:44
	ds_read2_b64 v[48:51], v53 offset0:72 offset1:76
	s_waitcnt lgkmcnt(1)
	v_mfma_f32_16x16x32_bf16 v[44:47], v[44:47], v[28:31], v[56:59]
	s_nop 2
	ds_read2_b64 v[56:59], v54 offset0:104 offset1:108
	s_waitcnt lgkmcnt(1)
	v_mfma_f32_16x16x32_bf16 v[48:51], v[48:51], v[28:31], v[102:105]
	s_nop 2
	ds_read2_b64 v[102:105], v55 offset0:40 offset1:44
	s_waitcnt lgkmcnt(1)
	v_mfma_f32_16x16x32_bf16 v[56:59], v[56:59], v[28:31], v[106:109]
	s_waitcnt lgkmcnt(0)
	v_mfma_f32_16x16x32_bf16 v[24:27], v[102:105], v[28:31], v[24:27]
	v_cvt_pk_bf16_f32 v28, v40, v41
	v_cvt_pk_bf16_f32 v29, v42, v43
	v_cvt_pk_bf16_f32 v30, v36, v37
	v_cvt_pk_bf16_f32 v31, v38, v39
	ds_read2_b64 v[36:39], v52 offset0:48 offset1:52
	ds_read2_b64 v[40:43], v53 offset0:80 offset1:84
	s_waitcnt lgkmcnt(1)
	v_mfma_f32_16x16x32_bf16 v[36:39], v[36:39], v[28:31], v[44:47]
	s_nop 2
	ds_read2_b64 v[44:47], v54 offset0:112 offset1:116
	s_waitcnt lgkmcnt(1)
	v_mfma_f32_16x16x32_bf16 v[40:43], v[40:43], v[28:31], v[48:51]
	s_nop 2
	ds_read2_b64 v[48:51], v55 offset0:48 offset1:52
	s_waitcnt lgkmcnt(1)
	v_mfma_f32_16x16x32_bf16 v[44:47], v[44:47], v[28:31], v[56:59]
	s_waitcnt lgkmcnt(0)
	v_mfma_f32_16x16x32_bf16 v[24:27], v[48:51], v[28:31], v[24:27]
	v_cvt_pk_bf16_f32 v48, v32, v33
	v_cvt_pk_bf16_f32 v49, v34, v35
	v_cvt_pk_bf16_f32 v50, v126, v127
	v_cvt_pk_bf16_f32 v51, v130, v131
	ds_read2_b64 v[28:31], v52 offset0:56 offset1:60
	s_waitcnt lgkmcnt(0)
	v_mfma_f32_16x16x32_bf16 v[36:39], v[28:31], v[48:51], v[36:39]
	ds_read2_b64 v[28:31], v53 offset0:88 offset1:92
	s_waitcnt lgkmcnt(0)
	v_mfma_f32_16x16x32_bf16 v[32:35], v[28:31], v[48:51], v[40:43]
	s_nop 2
	ds_read2_b64 v[40:43], v55 offset0:56 offset1:60
	ds_read2_b64 v[28:31], v54 offset0:120 offset1:124
	s_waitcnt lgkmcnt(1)
	v_mfma_f32_16x16x32_bf16 v[24:27], v[40:43], v[48:51], v[24:27]
	v_add_f32_e32 v40, v128, v129
	v_div_scale_f32 v41, s[8:9], v40, v40, 1.0
	v_rcp_f32_e32 v42, v41
	s_waitcnt lgkmcnt(0)
	v_mfma_f32_16x16x32_bf16 v[28:31], v[28:31], v[48:51], v[44:47]
	v_fma_f32 v43, -v41, v42, 1.0
	v_fmac_f32_e32 v42, v43, v42
	v_div_scale_f32 v43, vcc, 1.0, v40, 1.0
	v_mul_f32_e32 v44, v43, v42
	v_fma_f32 v45, -v41, v44, v43
	v_fmac_f32_e32 v44, v45, v42
	v_fma_f32 v41, -v41, v44, v43
	v_div_fmas_f32 v41, v41, v42, v44
	v_div_fixup_f32 v42, v41, v40, 1.0
	v_lshlrev_b64 v[40:41], 11, v[74:75]
	v_lshl_add_u64 v[40:41], s[66:67], 0, v[40:41]
	v_lshl_add_u64 v[40:41], v[40:41], 0, s[70:71]
	v_mul_f32_e32 v36, v42, v36
	v_mul_f32_e32 v37, v42, v37
	v_lshl_add_u64 v[40:41], v[40:41], 0, v[184:185]
	v_cvt_pk_bf16_f32 v36, v36, v37
	v_mul_f32_e32 v37, v42, v38
	v_mul_f32_e32 v32, v42, v32
	v_mul_f32_e32 v33, v42, v33
	v_mul_f32_e32 v38, v42, v39
	v_cvt_pk_bf16_f32 v37, v37, v38
	global_store_dwordx2 v[40:41], v[36:37], off offset:1536
	v_cvt_pk_bf16_f32 v32, v32, v33
	v_mul_f32_e32 v33, v42, v34
	v_mul_f32_e32 v28, v42, v28
	v_mul_f32_e32 v29, v42, v29
	v_mul_f32_e32 v34, v42, v35
	v_cvt_pk_bf16_f32 v33, v33, v34
	global_store_dwordx2 v[40:41], v[32:33], off offset:1568
	v_cvt_pk_bf16_f32 v28, v28, v29
	v_mul_f32_e32 v29, v42, v30
	v_mul_f32_e32 v24, v42, v24
	v_mul_f32_e32 v25, v42, v25
	v_mul_f32_e32 v30, v42, v31
	v_cvt_pk_bf16_f32 v29, v29, v30
	global_store_dwordx2 v[40:41], v[28:29], off offset:1600
	v_cvt_pk_bf16_f32 v24, v24, v25
	v_mul_f32_e32 v25, v42, v26
	v_mul_f32_e32 v26, v42, v27
	v_cvt_pk_bf16_f32 v25, v25, v26
	global_store_dwordx2 v[40:41], v[24:25], off offset:1632
	ds_read_b128 v[24:27], v95
	ds_read_b128 v[28:31], v95 offset:64
	s_waitcnt lgkmcnt(1)
	v_mfma_f32_16x16x32_bf16 v[24:27], v[24:27], v[16:19], 0
	s_waitcnt lgkmcnt(0)
	v_mfma_f32_16x16x32_bf16 v[56:59], v[28:31], v[20:23], v[24:27]
	s_nop 5
	ds_read_b128 v[24:27], v95 offset:2304
	ds_read_b128 v[28:31], v95 offset:2368
	s_waitcnt lgkmcnt(1)
	v_mfma_f32_16x16x32_bf16 v[24:27], v[24:27], v[16:19], 0
	s_waitcnt lgkmcnt(0)
	v_mfma_f32_16x16x32_bf16 v[102:105], v[28:31], v[20:23], v[24:27]
	s_nop 5
	ds_read_b128 v[24:27], v95 offset:4608
	ds_read_b128 v[28:31], v95 offset:4672
	s_waitcnt lgkmcnt(1)
	v_mfma_f32_16x16x32_bf16 v[24:27], v[24:27], v[16:19], 0
	s_waitcnt lgkmcnt(0)
	v_mfma_f32_16x16x32_bf16 v[106:109], v[28:31], v[20:23], v[24:27]
	s_nop 5
	ds_read_b128 v[24:27], v96
	ds_read_b128 v[28:31], v96 offset:64
	s_waitcnt lgkmcnt(1)
	v_mfma_f32_16x16x32_bf16 v[24:27], v[24:27], v[16:19], 0
	s_waitcnt lgkmcnt(0)
	v_mfma_f32_16x16x32_bf16 v[110:113], v[28:31], v[20:23], v[24:27]
	s_nop 5
	ds_read_b128 v[24:27], v95 offset:9216
	ds_read_b128 v[28:31], v95 offset:9280
	s_waitcnt lgkmcnt(1)
	v_mfma_f32_16x16x32_bf16 v[24:27], v[24:27], v[16:19], 0
	s_waitcnt lgkmcnt(0)
	v_mfma_f32_16x16x32_bf16 v[114:117], v[28:31], v[20:23], v[24:27]
	s_nop 5
	ds_read_b128 v[24:27], v95 offset:11520
	ds_read_b128 v[28:31], v95 offset:11584
	s_waitcnt lgkmcnt(1)
	v_mfma_f32_16x16x32_bf16 v[24:27], v[24:27], v[16:19], 0
	s_waitcnt lgkmcnt(0)
	v_mfma_f32_16x16x32_bf16 v[118:121], v[28:31], v[20:23], v[24:27]
	s_nop 5
	ds_read_b128 v[24:27], v95 offset:13824
	ds_read_b128 v[28:31], v95 offset:13888
	s_waitcnt lgkmcnt(1)
	v_mfma_f32_16x16x32_bf16 v[24:27], v[24:27], v[16:19], 0
	s_waitcnt lgkmcnt(0)
	v_mfma_f32_16x16x32_bf16 v[122:125], v[28:31], v[20:23], v[24:27]
	s_nop 5
	ds_read_b128 v[24:27], v97
	ds_read_b128 v[28:31], v97 offset:64
	s_waitcnt lgkmcnt(1)
	v_mfma_f32_16x16x32_bf16 v[24:27], v[24:27], v[16:19], 0
	s_waitcnt lgkmcnt(0)
	v_mfma_f32_16x16x32_bf16 v[126:129], v[28:31], v[20:23], v[24:27]
	s_nop 5
	ds_read_b128 v[24:27], v95 offset:18432
	ds_read_b128 v[28:31], v95 offset:18496
	s_waitcnt lgkmcnt(1)
	v_mfma_f32_16x16x32_bf16 v[24:27], v[24:27], v[16:19], 0
	s_waitcnt lgkmcnt(0)
	v_mfma_f32_16x16x32_bf16 v[48:51], v[28:31], v[20:23], v[24:27]
	s_nop 5
	ds_read_b128 v[24:27], v95 offset:20736
	ds_read_b128 v[28:31], v95 offset:20800
	s_waitcnt lgkmcnt(1)
	v_mfma_f32_16x16x32_bf16 v[24:27], v[24:27], v[16:19], 0
	s_waitcnt lgkmcnt(0)
	v_mfma_f32_16x16x32_bf16 v[44:47], v[28:31], v[20:23], v[24:27]
	s_nop 5
	ds_read_b128 v[24:27], v95 offset:23040
	ds_read_b128 v[28:31], v95 offset:23104
	s_waitcnt lgkmcnt(1)
	v_mfma_f32_16x16x32_bf16 v[24:27], v[24:27], v[16:19], 0
	s_waitcnt lgkmcnt(0)
	v_mfma_f32_16x16x32_bf16 v[40:43], v[28:31], v[20:23], v[24:27]
	s_nop 5
	ds_read_b128 v[24:27], v98
	ds_read_b128 v[28:31], v98 offset:64
	s_waitcnt lgkmcnt(1)
	v_mfma_f32_16x16x32_bf16 v[24:27], v[24:27], v[16:19], 0
	s_waitcnt lgkmcnt(0)
	v_mfma_f32_16x16x32_bf16 v[36:39], v[28:31], v[20:23], v[24:27]
	s_nop 5
	ds_read_b128 v[24:27], v95 offset:27648
	ds_read_b128 v[28:31], v95 offset:27712
	s_waitcnt lgkmcnt(1)
	v_mfma_f32_16x16x32_bf16 v[24:27], v[24:27], v[16:19], 0
	s_waitcnt lgkmcnt(0)
	v_mfma_f32_16x16x32_bf16 v[32:35], v[28:31], v[20:23], v[24:27]
	s_nop 5
	ds_read_b128 v[24:27], v95 offset:29952
	ds_read_b128 v[28:31], v95 offset:30016
	s_waitcnt lgkmcnt(1)
	v_mfma_f32_16x16x32_bf16 v[24:27], v[24:27], v[16:19], 0
	s_waitcnt lgkmcnt(0)
	v_mfma_f32_16x16x32_bf16 v[28:31], v[28:31], v[20:23], v[24:27]
	s_nop 5
	ds_read_b128 v[24:27], v95 offset:32256
	ds_read_b128 v[130:133], v95 offset:32320
	s_waitcnt lgkmcnt(1)
	v_mfma_f32_16x16x32_bf16 v[24:27], v[24:27], v[16:19], 0
	s_waitcnt lgkmcnt(0)
	v_mfma_f32_16x16x32_bf16 v[24:27], v[130:133], v[20:23], v[24:27]
	ds_read_b128 v[130:133], v99
	ds_read_b128 v[134:137], v99 offset:64
	s_waitcnt lgkmcnt(1)
	v_mfma_f32_16x16x32_bf16 v[16:19], v[130:133], v[16:19], 0
	s_waitcnt lgkmcnt(0)
	v_mfma_f32_16x16x32_bf16 v[16:19], v[134:137], v[20:23], v[16:19]
	v_max3_f32 v20, v56, v57, v58
	v_max_f32_e32 v21, v104, v104
	v_max_f32_e32 v22, v103, v103
	v_max3_f32 v20, v20, v59, v102
	v_max_f32_e32 v21, v22, v21
	v_max3_f32 v20, v20, v21, v105
	v_max_f32_e32 v21, v108, v108
	v_max_f32_e32 v22, v107, v107
	v_max_f32_e32 v21, v22, v21
	v_max3_f32 v20, v20, v106, v21
	v_max_f32_e32 v21, v112, v112
	v_max_f32_e32 v22, v111, v111
	v_max3_f32 v20, v20, v109, v110
	v_max_f32_e32 v21, v22, v21
	v_max3_f32 v20, v20, v21, v113
	v_max_f32_e32 v21, v116, v116
	v_max_f32_e32 v22, v115, v115
	v_max_f32_e32 v21, v22, v21
	v_max3_f32 v20, v20, v114, v21
	v_max_f32_e32 v21, v120, v120
	v_max_f32_e32 v22, v119, v119
	v_max3_f32 v20, v20, v117, v118
	v_max_f32_e32 v21, v22, v21
	v_max3_f32 v20, v20, v21, v121
	v_max_f32_e32 v21, v124, v124
	v_max_f32_e32 v22, v123, v123
	v_max_f32_e32 v21, v22, v21
	v_max3_f32 v20, v20, v122, v21
	v_max_f32_e32 v21, v128, v128
	v_max_f32_e32 v22, v127, v127
	v_max3_f32 v20, v20, v125, v126
	v_max_f32_e32 v21, v22, v21
	v_max3_f32 v20, v20, v21, v129
	v_max_f32_e32 v21, v50, v50
	v_max_f32_e32 v22, v49, v49
	v_max_f32_e32 v21, v22, v21
	v_max3_f32 v20, v20, v48, v21
	v_max_f32_e32 v21, v46, v46
	v_max_f32_e32 v22, v45, v45
	v_max3_f32 v20, v20, v51, v44
	v_max_f32_e32 v21, v22, v21
	v_max3_f32 v20, v20, v21, v47
	v_max_f32_e32 v21, v42, v42
	v_max_f32_e32 v22, v41, v41
	v_max_f32_e32 v21, v22, v21
	v_max3_f32 v20, v20, v40, v21
	v_max_f32_e32 v21, v38, v38
	v_max_f32_e32 v22, v37, v37
	v_max3_f32 v20, v20, v43, v36
	v_max_f32_e32 v21, v22, v21
	v_max3_f32 v20, v20, v21, v39
	v_max_f32_e32 v21, v34, v34
	v_max_f32_e32 v22, v33, v33
	v_max_f32_e32 v21, v22, v21
	v_max3_f32 v20, v20, v32, v21
	v_max_f32_e32 v21, v30, v30
	v_max_f32_e32 v22, v29, v29
	v_max3_f32 v20, v20, v35, v28
	v_max_f32_e32 v21, v22, v21
	v_max3_f32 v20, v20, v21, v31
	v_max_f32_e32 v21, v26, v26
	v_max_f32_e32 v22, v25, v25
	v_max_f32_e32 v21, v22, v21
	v_max3_f32 v20, v20, v24, v21
	v_max_f32_e32 v21, v18, v18
	v_max_f32_e32 v22, v17, v17
	v_max3_f32 v20, v20, v27, v16
	v_max_f32_e32 v21, v22, v21
	v_max3_f32 v20, v20, v21, v19
	ds_bpermute_b32 v21, v85, v20
	s_waitcnt lgkmcnt(0)
	v_max_f32_e32 v21, v21, v21
	v_max_f32_e32 v20, v20, v21
	ds_bpermute_b32 v21, v86, v20
	s_waitcnt lgkmcnt(0)
	v_max_f32_e32 v21, v21, v21
	v_max_f32_e32 v20, v20, v21
	v_sub_f32_e32 v21, v56, v20
	v_mul_f32_e32 v21, 0x3e38aa3b, v21
	v_sub_f32_e32 v23, v57, v20
	v_exp_f32_e32 v21, v21
	v_mul_f32_e32 v23, 0x3e38aa3b, v23
	v_sub_f32_e32 v56, v58, v20
	v_exp_f32_e32 v23, v23
	v_mul_f32_e32 v56, 0x3e38aa3b, v56
	v_sub_f32_e32 v57, v59, v20
	v_exp_f32_e32 v56, v56
	v_mul_f32_e32 v57, 0x3e38aa3b, v57
	v_sub_f32_e32 v58, v102, v20
	v_exp_f32_e32 v57, v57
	v_mul_f32_e32 v58, 0x3e38aa3b, v58
	v_sub_f32_e32 v59, v103, v20
	v_add_f32_e32 v22, 0, v21
	v_exp_f32_e32 v58, v58
	v_mul_f32_e32 v59, 0x3e38aa3b, v59
	v_sub_f32_e32 v74, v104, v20
	v_add_f32_e32 v22, v23, v22
	v_exp_f32_e32 v59, v59
	v_mul_f32_e32 v74, 0x3e38aa3b, v74
	v_sub_f32_e32 v75, v105, v20
	v_add_f32_e32 v22, v56, v22
	v_exp_f32_e32 v74, v74
	v_mul_f32_e32 v75, 0x3e38aa3b, v75
	v_sub_f32_e32 v102, v106, v20
	v_add_f32_e32 v22, v57, v22
	v_exp_f32_e32 v75, v75
	v_mul_f32_e32 v102, 0x3e38aa3b, v102
	v_sub_f32_e32 v103, v107, v20
	v_add_f32_e32 v22, v58, v22
	v_exp_f32_e32 v102, v102
	v_mul_f32_e32 v103, 0x3e38aa3b, v103
	v_sub_f32_e32 v104, v108, v20
	v_add_f32_e32 v22, v59, v22
	v_exp_f32_e32 v103, v103
	v_mul_f32_e32 v104, 0x3e38aa3b, v104
	v_sub_f32_e32 v105, v109, v20
	v_add_f32_e32 v22, v74, v22
	v_exp_f32_e32 v104, v104
	v_mul_f32_e32 v105, 0x3e38aa3b, v105
	v_sub_f32_e32 v106, v110, v20
	v_add_f32_e32 v22, v75, v22
	v_exp_f32_e32 v105, v105
	v_mul_f32_e32 v106, 0x3e38aa3b, v106
	v_sub_f32_e32 v107, v111, v20
	v_add_f32_e32 v22, v102, v22
	v_exp_f32_e32 v106, v106
	v_mul_f32_e32 v107, 0x3e38aa3b, v107
	v_sub_f32_e32 v108, v112, v20
	v_add_f32_e32 v22, v103, v22
	v_exp_f32_e32 v107, v107
	v_mul_f32_e32 v108, 0x3e38aa3b, v108
	v_sub_f32_e32 v109, v113, v20
	v_add_f32_e32 v22, v104, v22
	v_exp_f32_e32 v108, v108
	v_mul_f32_e32 v109, 0x3e38aa3b, v109
	v_sub_f32_e32 v110, v114, v20
	v_add_f32_e32 v22, v105, v22
	v_exp_f32_e32 v109, v109
	v_mul_f32_e32 v110, 0x3e38aa3b, v110
	v_sub_f32_e32 v111, v115, v20
	v_add_f32_e32 v22, v106, v22
	v_exp_f32_e32 v110, v110
	v_mul_f32_e32 v111, 0x3e38aa3b, v111
	v_sub_f32_e32 v112, v116, v20
	v_add_f32_e32 v22, v107, v22
	v_exp_f32_e32 v111, v111
	v_mul_f32_e32 v112, 0x3e38aa3b, v112
	v_sub_f32_e32 v113, v117, v20
	v_add_f32_e32 v22, v108, v22
	v_exp_f32_e32 v112, v112
	v_mul_f32_e32 v113, 0x3e38aa3b, v113
	v_sub_f32_e32 v114, v118, v20
	v_add_f32_e32 v22, v109, v22
	v_exp_f32_e32 v113, v113
	v_mul_f32_e32 v114, 0x3e38aa3b, v114
	v_sub_f32_e32 v115, v119, v20
	v_add_f32_e32 v22, v110, v22
	v_exp_f32_e32 v114, v114
	v_mul_f32_e32 v115, 0x3e38aa3b, v115
	v_sub_f32_e32 v116, v120, v20
	v_add_f32_e32 v22, v111, v22
	v_exp_f32_e32 v115, v115
	v_mul_f32_e32 v116, 0x3e38aa3b, v116
	v_sub_f32_e32 v117, v121, v20
	v_add_f32_e32 v22, v112, v22
	v_exp_f32_e32 v116, v116
	v_mul_f32_e32 v117, 0x3e38aa3b, v117
	v_sub_f32_e32 v118, v122, v20
	v_add_f32_e32 v22, v113, v22
	v_exp_f32_e32 v117, v117
	v_mul_f32_e32 v118, 0x3e38aa3b, v118
	v_sub_f32_e32 v119, v123, v20
	v_add_f32_e32 v22, v114, v22
	v_exp_f32_e32 v118, v118
	v_mul_f32_e32 v119, 0x3e38aa3b, v119
	v_sub_f32_e32 v120, v124, v20
	v_add_f32_e32 v22, v115, v22
	v_exp_f32_e32 v119, v119
	v_mul_f32_e32 v120, 0x3e38aa3b, v120
	v_sub_f32_e32 v121, v125, v20
	v_add_f32_e32 v22, v116, v22
	v_exp_f32_e32 v120, v120
	v_mul_f32_e32 v121, 0x3e38aa3b, v121
	v_sub_f32_e32 v122, v126, v20
	v_add_f32_e32 v22, v117, v22
	v_exp_f32_e32 v121, v121
	v_mul_f32_e32 v122, 0x3e38aa3b, v122
	v_sub_f32_e32 v123, v127, v20
	v_add_f32_e32 v22, v118, v22
	v_exp_f32_e32 v122, v122
	v_mul_f32_e32 v123, 0x3e38aa3b, v123
	v_sub_f32_e32 v124, v128, v20
	v_add_f32_e32 v22, v119, v22
	v_exp_f32_e32 v123, v123
	v_mul_f32_e32 v124, 0x3e38aa3b, v124
	v_sub_f32_e32 v125, v129, v20
	v_add_f32_e32 v22, v120, v22
	v_exp_f32_e32 v124, v124
	v_mul_f32_e32 v125, 0x3e38aa3b, v125
	v_sub_f32_e32 v48, v48, v20
	v_add_f32_e32 v22, v121, v22
	v_exp_f32_e32 v125, v125
	v_mul_f32_e32 v48, 0x3e38aa3b, v48
	v_sub_f32_e32 v49, v49, v20
	v_add_f32_e32 v22, v122, v22
	v_exp_f32_e32 v48, v48
	v_mul_f32_e32 v49, 0x3e38aa3b, v49
	v_sub_f32_e32 v50, v50, v20
	v_add_f32_e32 v22, v123, v22
	v_exp_f32_e32 v49, v49
	v_mul_f32_e32 v50, 0x3e38aa3b, v50
	v_sub_f32_e32 v51, v51, v20
	v_add_f32_e32 v22, v124, v22
	v_exp_f32_e32 v50, v50
	v_mul_f32_e32 v51, 0x3e38aa3b, v51
	v_sub_f32_e32 v44, v44, v20
	v_add_f32_e32 v22, v125, v22
	v_exp_f32_e32 v51, v51
	v_mul_f32_e32 v44, 0x3e38aa3b, v44
	v_sub_f32_e32 v45, v45, v20
	v_add_f32_e32 v22, v48, v22
	v_exp_f32_e32 v44, v44
	v_mul_f32_e32 v45, 0x3e38aa3b, v45
	v_sub_f32_e32 v46, v46, v20
	v_add_f32_e32 v22, v49, v22
	v_exp_f32_e32 v45, v45
	v_mul_f32_e32 v46, 0x3e38aa3b, v46
	v_sub_f32_e32 v47, v47, v20
	v_add_f32_e32 v22, v50, v22
	v_exp_f32_e32 v46, v46
	v_mul_f32_e32 v47, 0x3e38aa3b, v47
	v_sub_f32_e32 v40, v40, v20
	v_add_f32_e32 v22, v51, v22
	v_exp_f32_e32 v47, v47
	v_mul_f32_e32 v40, 0x3e38aa3b, v40
	v_sub_f32_e32 v41, v41, v20
	v_sub_f32_e32 v36, v36, v20
	v_add_f32_e32 v22, v44, v22
	v_exp_f32_e32 v40, v40
	v_mul_f32_e32 v41, 0x3e38aa3b, v41
	v_sub_f32_e32 v42, v42, v20
	v_mul_f32_e32 v36, 0x3e38aa3b, v36
	v_add_f32_e32 v22, v45, v22
	v_exp_f32_e32 v41, v41
	v_mul_f32_e32 v42, 0x3e38aa3b, v42
	v_sub_f32_e32 v43, v43, v20
	v_exp_f32_e32 v126, v36
	v_sub_f32_e32 v36, v37, v20
	v_add_f32_e32 v22, v46, v22
	v_exp_f32_e32 v42, v42
	v_mul_f32_e32 v43, 0x3e38aa3b, v43
	v_mul_f32_e32 v36, 0x3e38aa3b, v36
	v_add_f32_e32 v22, v47, v22
	v_exp_f32_e32 v43, v43
	v_exp_f32_e32 v127, v36
	v_sub_f32_e32 v36, v38, v20
	v_sub_f32_e32 v32, v32, v20
	v_add_f32_e32 v22, v40, v22
	v_mul_f32_e32 v36, 0x3e38aa3b, v36
	v_mul_f32_e32 v32, 0x3e38aa3b, v32
	v_add_f32_e32 v22, v41, v22
	v_exp_f32_e32 v128, v36
	v_sub_f32_e32 v36, v39, v20
	v_exp_f32_e32 v130, v32
	v_sub_f32_e32 v32, v33, v20
	v_add_f32_e32 v22, v42, v22
	v_mul_f32_e32 v36, 0x3e38aa3b, v36
	v_mul_f32_e32 v32, 0x3e38aa3b, v32
	v_add_f32_e32 v22, v43, v22
	v_exp_f32_e32 v129, v36
	v_exp_f32_e32 v131, v32
	v_sub_f32_e32 v32, v34, v20
	v_sub_f32_e32 v28, v28, v20
	v_add_f32_e32 v22, v126, v22
	v_mul_f32_e32 v32, 0x3e38aa3b, v32
	v_mul_f32_e32 v28, 0x3e38aa3b, v28
	v_add_f32_e32 v22, v127, v22
	v_exp_f32_e32 v132, v32
	v_sub_f32_e32 v32, v35, v20
	v_exp_f32_e32 v134, v28
	v_sub_f32_e32 v28, v29, v20
	v_add_f32_e32 v22, v128, v22
	v_mul_f32_e32 v32, 0x3e38aa3b, v32
	v_mul_f32_e32 v28, 0x3e38aa3b, v28
	v_add_f32_e32 v22, v129, v22
	v_exp_f32_e32 v133, v32
	v_exp_f32_e32 v135, v28
	v_sub_f32_e32 v28, v30, v20
	v_sub_f32_e32 v24, v24, v20
	v_add_f32_e32 v22, v130, v22
	v_mul_f32_e32 v28, 0x3e38aa3b, v28
	v_mul_f32_e32 v24, 0x3e38aa3b, v24
	v_add_f32_e32 v22, v131, v22
	v_exp_f32_e32 v136, v28
	v_sub_f32_e32 v28, v31, v20
	v_exp_f32_e32 v138, v24
	v_sub_f32_e32 v24, v25, v20
	v_add_f32_e32 v22, v132, v22
	v_mul_f32_e32 v28, 0x3e38aa3b, v28
	v_mul_f32_e32 v24, 0x3e38aa3b, v24
	v_add_f32_e32 v22, v133, v22
	v_exp_f32_e32 v137, v28
	v_exp_f32_e32 v139, v24
	v_sub_f32_e32 v24, v26, v20
	v_add_f32_e32 v22, v134, v22
	v_mul_f32_e32 v24, 0x3e38aa3b, v24
	v_add_f32_e32 v22, v135, v22
	v_exp_f32_e32 v140, v24
	v_sub_f32_e32 v24, v27, v20
	v_sub_f32_e32 v17, v17, v20
	v_add_f32_e32 v22, v136, v22
	v_mul_f32_e32 v24, 0x3e38aa3b, v24
	v_sub_f32_e32 v16, v16, v20
	v_mul_f32_e32 v17, 0x3e38aa3b, v17
	v_add_f32_e32 v22, v137, v22
	v_exp_f32_e32 v141, v24
	v_mul_f32_e32 v16, 0x3e38aa3b, v16
	v_exp_f32_e32 v143, v17
	v_sub_f32_e32 v17, v18, v20
	v_add_f32_e32 v22, v138, v22
	v_exp_f32_e32 v142, v16
	v_mul_f32_e32 v17, 0x3e38aa3b, v17
	v_add_f32_e32 v22, v139, v22
	v_exp_f32_e32 v144, v17
	v_sub_f32_e32 v17, v19, v20
	v_add_f32_e32 v22, v140, v22
	v_mul_f32_e32 v17, 0x3e38aa3b, v17
	v_add_f32_e32 v22, v141, v22
	v_exp_f32_e32 v145, v17
	v_add_f32_e32 v16, v142, v22
	v_add_f32_e32 v16, v143, v16
	v_add_f32_e32 v16, v144, v16
	v_add_f32_e32 v16, v145, v16
	ds_bpermute_b32 v17, v85, v16
	s_waitcnt lgkmcnt(0)
	v_add_f32_e32 v146, v16, v17
	v_cvt_pk_bf16_f32 v16, v21, v23
	v_cvt_pk_bf16_f32 v17, v56, v57
	v_cvt_pk_bf16_f32 v18, v58, v59
	v_cvt_pk_bf16_f32 v19, v74, v75
	ds_read2_b64 v[20:23], v52 offset1:4
	ds_read2_b64 v[24:27], v53 offset0:32 offset1:36
	ds_read2_b64 v[28:31], v54 offset0:64 offset1:68
	ds_read2_b64 v[32:35], v55 offset1:4
	s_waitcnt lgkmcnt(3)
	v_mfma_f32_16x16x32_bf16 v[20:23], v[20:23], v[16:19], 0
	ds_bpermute_b32 v147, v86, v146
	s_waitcnt lgkmcnt(3)
	v_mfma_f32_16x16x32_bf16 v[24:27], v[24:27], v[16:19], 0
	s_waitcnt lgkmcnt(2)
	v_mfma_f32_16x16x32_bf16 v[28:31], v[28:31], v[16:19], 0
	s_waitcnt lgkmcnt(1)
	v_mfma_f32_16x16x32_bf16 v[16:19], v[32:35], v[16:19], 0
	v_cvt_pk_bf16_f32 v32, v102, v103
	v_cvt_pk_bf16_f32 v33, v104, v105
	v_cvt_pk_bf16_f32 v34, v106, v107
	v_cvt_pk_bf16_f32 v35, v108, v109
	ds_read2_b64 v[36:39], v52 offset0:8 offset1:12
	s_waitcnt lgkmcnt(0)
	v_mfma_f32_16x16x32_bf16 v[20:23], v[36:39], v[32:35], v[20:23]
	ds_read2_b64 v[36:39], v53 offset0:40 offset1:44
	s_waitcnt lgkmcnt(0)
	v_mfma_f32_16x16x32_bf16 v[24:27], v[36:39], v[32:35], v[24:27]
	ds_read2_b64 v[36:39], v54 offset0:72 offset1:76
	s_waitcnt lgkmcnt(0)
	v_mfma_f32_16x16x32_bf16 v[28:31], v[36:39], v[32:35], v[28:31]
	ds_read2_b64 v[36:39], v55 offset0:8 offset1:12
	s_waitcnt lgkmcnt(0)
	v_mfma_f32_16x16x32_bf16 v[16:19], v[36:39], v[32:35], v[16:19]
	v_cvt_pk_bf16_f32 v32, v110, v111
	v_cvt_pk_bf16_f32 v33, v112, v113
	v_cvt_pk_bf16_f32 v34, v114, v115
	v_cvt_pk_bf16_f32 v35, v116, v117
	ds_read2_b64 v[36:39], v52 offset0:16 offset1:20
	s_waitcnt lgkmcnt(0)
	v_mfma_f32_16x16x32_bf16 v[20:23], v[36:39], v[32:35], v[20:23]
	ds_read2_b64 v[36:39], v53 offset0:48 offset1:52
	s_waitcnt lgkmcnt(0)
	v_mfma_f32_16x16x32_bf16 v[24:27], v[36:39], v[32:35], v[24:27]
	ds_read2_b64 v[36:39], v54 offset0:80 offset1:84
	s_waitcnt lgkmcnt(0)
	v_mfma_f32_16x16x32_bf16 v[28:31], v[36:39], v[32:35], v[28:31]
	ds_read2_b64 v[36:39], v55 offset0:16 offset1:20
	s_waitcnt lgkmcnt(0)
	v_mfma_f32_16x16x32_bf16 v[16:19], v[36:39], v[32:35], v[16:19]
	v_cvt_pk_bf16_f32 v32, v118, v119
	v_cvt_pk_bf16_f32 v33, v120, v121
	v_cvt_pk_bf16_f32 v34, v122, v123
	v_cvt_pk_bf16_f32 v35, v124, v125
	ds_read2_b64 v[36:39], v52 offset0:24 offset1:28
	s_waitcnt lgkmcnt(0)
	v_mfma_f32_16x16x32_bf16 v[20:23], v[36:39], v[32:35], v[20:23]
	ds_read2_b64 v[36:39], v53 offset0:56 offset1:60
	s_waitcnt lgkmcnt(0)
	v_mfma_f32_16x16x32_bf16 v[24:27], v[36:39], v[32:35], v[24:27]
	ds_read2_b64 v[36:39], v54 offset0:88 offset1:92
	s_waitcnt lgkmcnt(0)
	v_mfma_f32_16x16x32_bf16 v[28:31], v[36:39], v[32:35], v[28:31]
	ds_read2_b64 v[36:39], v55 offset0:24 offset1:28
	s_waitcnt lgkmcnt(0)
	v_mfma_f32_16x16x32_bf16 v[16:19], v[36:39], v[32:35], v[16:19]
	v_cvt_pk_bf16_f32 v32, v48, v49
	v_cvt_pk_bf16_f32 v33, v50, v51
	v_cvt_pk_bf16_f32 v34, v44, v45
	v_cvt_pk_bf16_f32 v35, v46, v47
	ds_read2_b64 v[36:39], v52 offset0:32 offset1:36
	s_waitcnt lgkmcnt(0)
	v_mfma_f32_16x16x32_bf16 v[20:23], v[36:39], v[32:35], v[20:23]
	ds_read2_b64 v[36:39], v53 offset0:64 offset1:68
	s_waitcnt lgkmcnt(0)
	v_mfma_f32_16x16x32_bf16 v[24:27], v[36:39], v[32:35], v[24:27]
	ds_read2_b64 v[36:39], v54 offset0:96 offset1:100
	s_waitcnt lgkmcnt(0)
	v_mfma_f32_16x16x32_bf16 v[28:31], v[36:39], v[32:35], v[28:31]
	ds_read2_b64 v[36:39], v55 offset0:32 offset1:36
	s_waitcnt lgkmcnt(0)
	v_mfma_f32_16x16x32_bf16 v[16:19], v[36:39], v[32:35], v[16:19]
	v_cvt_pk_bf16_f32 v32, v40, v41
	v_cvt_pk_bf16_f32 v33, v42, v43
	v_cvt_pk_bf16_f32 v34, v126, v127
	v_cvt_pk_bf16_f32 v35, v128, v129
	ds_read2_b64 v[36:39], v52 offset0:40 offset1:44
	s_waitcnt lgkmcnt(0)
	v_mfma_f32_16x16x32_bf16 v[20:23], v[36:39], v[32:35], v[20:23]
	ds_read2_b64 v[36:39], v53 offset0:72 offset1:76
	s_waitcnt lgkmcnt(0)
	v_mfma_f32_16x16x32_bf16 v[24:27], v[36:39], v[32:35], v[24:27]
	ds_read2_b64 v[36:39], v54 offset0:104 offset1:108
	s_waitcnt lgkmcnt(0)
	v_mfma_f32_16x16x32_bf16 v[28:31], v[36:39], v[32:35], v[28:31]
	ds_read2_b64 v[36:39], v55 offset0:40 offset1:44
	s_waitcnt lgkmcnt(0)
	v_mfma_f32_16x16x32_bf16 v[16:19], v[36:39], v[32:35], v[16:19]
	v_cvt_pk_bf16_f32 v32, v130, v131
	v_cvt_pk_bf16_f32 v33, v132, v133
	v_cvt_pk_bf16_f32 v34, v134, v135
	v_cvt_pk_bf16_f32 v35, v136, v137
	ds_read2_b64 v[36:39], v52 offset0:48 offset1:52
	s_waitcnt lgkmcnt(0)
	v_mfma_f32_16x16x32_bf16 v[20:23], v[36:39], v[32:35], v[20:23]
	ds_read2_b64 v[36:39], v53 offset0:80 offset1:84
	s_waitcnt lgkmcnt(0)
	v_mfma_f32_16x16x32_bf16 v[24:27], v[36:39], v[32:35], v[24:27]
	ds_read2_b64 v[36:39], v54 offset0:112 offset1:116
	s_waitcnt lgkmcnt(0)
	v_mfma_f32_16x16x32_bf16 v[36:39], v[36:39], v[32:35], v[28:31]
	s_nop 2
	ds_read2_b64 v[28:31], v55 offset0:48 offset1:52
	s_waitcnt lgkmcnt(0)
	v_mfma_f32_16x16x32_bf16 v[16:19], v[28:31], v[32:35], v[16:19]
	v_cvt_pk_bf16_f32 v32, v138, v139
	v_cvt_pk_bf16_f32 v33, v140, v141
	v_cvt_pk_bf16_f32 v34, v142, v143
	v_cvt_pk_bf16_f32 v35, v144, v145
	ds_read2_b64 v[28:31], v52 offset0:56 offset1:60
	s_waitcnt lgkmcnt(0)
	v_mfma_f32_16x16x32_bf16 v[28:31], v[28:31], v[32:35], v[20:23]
	s_nop 2
	ds_read2_b64 v[20:23], v53 offset0:88 offset1:92
	s_waitcnt lgkmcnt(0)
	v_mfma_f32_16x16x32_bf16 v[24:27], v[20:23], v[32:35], v[24:27]
	ds_read2_b64 v[20:23], v54 offset0:120 offset1:124
	s_waitcnt lgkmcnt(0)
	v_mfma_f32_16x16x32_bf16 v[20:23], v[20:23], v[32:35], v[36:39]
	s_nop 2
	ds_read2_b64 v[36:39], v55 offset0:56 offset1:60
	s_waitcnt lgkmcnt(0)
	v_mfma_f32_16x16x32_bf16 v[16:19], v[36:39], v[32:35], v[16:19]
	v_add_f32_e32 v32, v146, v147
	v_div_scale_f32 v33, s[8:9], v32, v32, 1.0
	v_rcp_f32_e32 v34, v33
	s_nop 0
	v_fma_f32 v35, -v33, v34, 1.0
	v_fmac_f32_e32 v34, v35, v34
	v_div_scale_f32 v35, vcc, 1.0, v32, 1.0
	v_mul_f32_e32 v36, v35, v34
	v_fma_f32 v37, -v33, v36, v35
	v_fmac_f32_e32 v36, v37, v34
	v_fma_f32 v33, -v33, v36, v35
	v_div_fmas_f32 v33, v33, v34, v36
	v_div_fixup_f32 v34, v33, v32, 1.0
	v_lshlrev_b64 v[32:33], 11, v[72:73]
	v_lshl_add_u64 v[32:33], s[66:67], 0, v[32:33]
	v_lshl_add_u64 v[32:33], v[32:33], 0, s[70:71]
	v_mul_f32_e32 v28, v34, v28
	v_mul_f32_e32 v29, v34, v29
	v_lshl_add_u64 v[32:33], v[32:33], 0, v[184:185]
	v_cvt_pk_bf16_f32 v28, v28, v29
	v_mul_f32_e32 v29, v34, v30
	v_mul_f32_e32 v24, v34, v24
	v_mul_f32_e32 v25, v34, v25
	v_mul_f32_e32 v30, v34, v31
	v_cvt_pk_bf16_f32 v29, v29, v30
	global_store_dwordx2 v[32:33], v[28:29], off offset:1536
	v_cvt_pk_bf16_f32 v24, v24, v25
	v_mul_f32_e32 v25, v34, v26
	v_mul_f32_e32 v20, v34, v20
	v_mul_f32_e32 v21, v34, v21
	v_mul_f32_e32 v26, v34, v27
	v_cvt_pk_bf16_f32 v25, v25, v26
	global_store_dwordx2 v[32:33], v[24:25], off offset:1568
	v_cvt_pk_bf16_f32 v20, v20, v21
	v_mul_f32_e32 v21, v34, v22
	v_mul_f32_e32 v16, v34, v16
	v_mul_f32_e32 v17, v34, v17
	v_mul_f32_e32 v22, v34, v23
	v_cvt_pk_bf16_f32 v21, v21, v22
	global_store_dwordx2 v[32:33], v[20:21], off offset:1600
	v_cvt_pk_bf16_f32 v16, v16, v17
	v_mul_f32_e32 v17, v34, v18
	v_mul_f32_e32 v18, v34, v19
	v_cvt_pk_bf16_f32 v17, v17, v18
	global_store_dwordx2 v[32:33], v[16:17], off offset:1632
	ds_read_b128 v[16:19], v95
	ds_read_b128 v[20:23], v95 offset:64
	s_waitcnt lgkmcnt(1)
	v_mfma_f32_16x16x32_bf16 v[16:19], v[16:19], v[8:11], 0
	s_waitcnt lgkmcnt(0)
	v_mfma_f32_16x16x32_bf16 v[44:47], v[20:23], v[12:15], v[16:19]
	s_nop 5
	ds_read_b128 v[16:19], v95 offset:2304
	ds_read_b128 v[20:23], v95 offset:2368
	s_waitcnt lgkmcnt(1)
	v_mfma_f32_16x16x32_bf16 v[16:19], v[16:19], v[8:11], 0
	s_waitcnt lgkmcnt(0)
	v_mfma_f32_16x16x32_bf16 v[48:51], v[20:23], v[12:15], v[16:19]
	s_nop 5
	ds_read_b128 v[16:19], v95 offset:4608
	ds_read_b128 v[20:23], v95 offset:4672
	s_waitcnt lgkmcnt(1)
	v_mfma_f32_16x16x32_bf16 v[16:19], v[16:19], v[8:11], 0
	s_waitcnt lgkmcnt(0)
	v_mfma_f32_16x16x32_bf16 v[56:59], v[20:23], v[12:15], v[16:19]
	s_nop 5
	ds_read_b128 v[16:19], v96
	ds_read_b128 v[20:23], v96 offset:64
	s_waitcnt lgkmcnt(1)
	v_mfma_f32_16x16x32_bf16 v[16:19], v[16:19], v[8:11], 0
	s_waitcnt lgkmcnt(0)
	v_mfma_f32_16x16x32_bf16 v[72:75], v[20:23], v[12:15], v[16:19]
	s_nop 5
	ds_read_b128 v[16:19], v95 offset:9216
	ds_read_b128 v[20:23], v95 offset:9280
	s_waitcnt lgkmcnt(1)
	v_mfma_f32_16x16x32_bf16 v[16:19], v[16:19], v[8:11], 0
	s_waitcnt lgkmcnt(0)
	v_mfma_f32_16x16x32_bf16 v[102:105], v[20:23], v[12:15], v[16:19]
	s_nop 5
	ds_read_b128 v[16:19], v95 offset:11520
	ds_read_b128 v[20:23], v95 offset:11584
	s_waitcnt lgkmcnt(1)
	v_mfma_f32_16x16x32_bf16 v[16:19], v[16:19], v[8:11], 0
	s_waitcnt lgkmcnt(0)
	v_mfma_f32_16x16x32_bf16 v[106:109], v[20:23], v[12:15], v[16:19]
	s_nop 5
	ds_read_b128 v[16:19], v95 offset:13824
	ds_read_b128 v[20:23], v95 offset:13888
	s_waitcnt lgkmcnt(1)
	v_mfma_f32_16x16x32_bf16 v[16:19], v[16:19], v[8:11], 0
	s_waitcnt lgkmcnt(0)
	v_mfma_f32_16x16x32_bf16 v[110:113], v[20:23], v[12:15], v[16:19]
	s_nop 5
	ds_read_b128 v[16:19], v97
	ds_read_b128 v[20:23], v97 offset:64
	s_waitcnt lgkmcnt(1)
	v_mfma_f32_16x16x32_bf16 v[16:19], v[16:19], v[8:11], 0
	s_waitcnt lgkmcnt(0)
	v_mfma_f32_16x16x32_bf16 v[114:117], v[20:23], v[12:15], v[16:19]
	s_nop 5
	ds_read_b128 v[16:19], v95 offset:18432
	ds_read_b128 v[20:23], v95 offset:18496
	s_waitcnt lgkmcnt(1)
	v_mfma_f32_16x16x32_bf16 v[16:19], v[16:19], v[8:11], 0
	s_waitcnt lgkmcnt(0)
	v_mfma_f32_16x16x32_bf16 v[40:43], v[20:23], v[12:15], v[16:19]
	s_nop 5
	ds_read_b128 v[16:19], v95 offset:20736
	ds_read_b128 v[20:23], v95 offset:20800
	s_waitcnt lgkmcnt(1)
	v_mfma_f32_16x16x32_bf16 v[16:19], v[16:19], v[8:11], 0
	s_waitcnt lgkmcnt(0)
	v_mfma_f32_16x16x32_bf16 v[36:39], v[20:23], v[12:15], v[16:19]
	s_nop 5
	ds_read_b128 v[16:19], v95 offset:23040
	ds_read_b128 v[20:23], v95 offset:23104
	s_waitcnt lgkmcnt(1)
	v_mfma_f32_16x16x32_bf16 v[16:19], v[16:19], v[8:11], 0
	s_waitcnt lgkmcnt(0)
	v_mfma_f32_16x16x32_bf16 v[32:35], v[20:23], v[12:15], v[16:19]
	s_nop 5
	ds_read_b128 v[16:19], v98
	ds_read_b128 v[20:23], v98 offset:64
	s_waitcnt lgkmcnt(1)
	v_mfma_f32_16x16x32_bf16 v[16:19], v[16:19], v[8:11], 0
	s_waitcnt lgkmcnt(0)
	v_mfma_f32_16x16x32_bf16 v[28:31], v[20:23], v[12:15], v[16:19]
	s_nop 5
	ds_read_b128 v[16:19], v95 offset:27648
	ds_read_b128 v[20:23], v95 offset:27712
	s_waitcnt lgkmcnt(1)
	v_mfma_f32_16x16x32_bf16 v[16:19], v[16:19], v[8:11], 0
	s_waitcnt lgkmcnt(0)
	v_mfma_f32_16x16x32_bf16 v[24:27], v[20:23], v[12:15], v[16:19]
	s_nop 5
	ds_read_b128 v[16:19], v95 offset:29952
	ds_read_b128 v[20:23], v95 offset:30016
	s_waitcnt lgkmcnt(1)
	v_mfma_f32_16x16x32_bf16 v[16:19], v[16:19], v[8:11], 0
	s_waitcnt lgkmcnt(0)
	v_mfma_f32_16x16x32_bf16 v[20:23], v[20:23], v[12:15], v[16:19]
	s_nop 5
	ds_read_b128 v[16:19], v95 offset:32256
	ds_read_b128 v[118:121], v95 offset:32320
	s_waitcnt lgkmcnt(1)
	v_mfma_f32_16x16x32_bf16 v[16:19], v[16:19], v[8:11], 0
	s_waitcnt lgkmcnt(0)
	v_mfma_f32_16x16x32_bf16 v[16:19], v[118:121], v[12:15], v[16:19]
	ds_read_b128 v[118:121], v99
	ds_read_b128 v[122:125], v99 offset:64
	s_waitcnt lgkmcnt(1)
	v_mfma_f32_16x16x32_bf16 v[8:11], v[118:121], v[8:11], 0
	s_waitcnt lgkmcnt(0)
	v_mfma_f32_16x16x32_bf16 v[8:11], v[122:125], v[12:15], v[8:11]
	v_max3_f32 v12, v44, v45, v46
	v_max_f32_e32 v13, v50, v50
	v_max_f32_e32 v14, v49, v49
	v_max3_f32 v12, v12, v47, v48
	v_max_f32_e32 v13, v14, v13
	v_max3_f32 v12, v12, v13, v51
	v_max_f32_e32 v13, v58, v58
	v_max_f32_e32 v14, v57, v57
	v_max_f32_e32 v13, v14, v13
	v_max3_f32 v12, v12, v56, v13
	v_max_f32_e32 v13, v74, v74
	v_max_f32_e32 v14, v73, v73
	v_max3_f32 v12, v12, v59, v72
	v_max_f32_e32 v13, v14, v13
	v_max3_f32 v12, v12, v13, v75
	v_max_f32_e32 v13, v104, v104
	v_max_f32_e32 v14, v103, v103
	v_max_f32_e32 v13, v14, v13
	v_max3_f32 v12, v12, v102, v13
	v_max_f32_e32 v13, v108, v108
	v_max_f32_e32 v14, v107, v107
	v_max3_f32 v12, v12, v105, v106
	v_max_f32_e32 v13, v14, v13
	v_max3_f32 v12, v12, v13, v109
	v_max_f32_e32 v13, v112, v112
	v_max_f32_e32 v14, v111, v111
	v_max_f32_e32 v13, v14, v13
	v_max3_f32 v12, v12, v110, v13
	v_max_f32_e32 v13, v116, v116
	v_max_f32_e32 v14, v115, v115
	v_max3_f32 v12, v12, v113, v114
	v_max_f32_e32 v13, v14, v13
	v_max3_f32 v12, v12, v13, v117
	v_max_f32_e32 v13, v42, v42
	v_max_f32_e32 v14, v41, v41
	v_max_f32_e32 v13, v14, v13
	v_max3_f32 v12, v12, v40, v13
	v_max_f32_e32 v13, v38, v38
	v_max_f32_e32 v14, v37, v37
	v_max3_f32 v12, v12, v43, v36
	v_max_f32_e32 v13, v14, v13
	v_max3_f32 v12, v12, v13, v39
	v_max_f32_e32 v13, v34, v34
	v_max_f32_e32 v14, v33, v33
	v_max_f32_e32 v13, v14, v13
	v_max3_f32 v12, v12, v32, v13
	v_max_f32_e32 v13, v30, v30
	v_max_f32_e32 v14, v29, v29
	v_max3_f32 v12, v12, v35, v28
	v_max_f32_e32 v13, v14, v13
	v_max3_f32 v12, v12, v13, v31
	v_max_f32_e32 v13, v26, v26
	v_max_f32_e32 v14, v25, v25
	v_max_f32_e32 v13, v14, v13
	v_max3_f32 v12, v12, v24, v13
	v_max_f32_e32 v13, v22, v22
	v_max_f32_e32 v14, v21, v21
	v_max3_f32 v12, v12, v27, v20
	v_max_f32_e32 v13, v14, v13
	v_max3_f32 v12, v12, v13, v23
	v_max_f32_e32 v13, v18, v18
	v_max_f32_e32 v14, v17, v17
	v_max_f32_e32 v13, v14, v13
	v_max3_f32 v12, v12, v16, v13
	v_max_f32_e32 v13, v10, v10
	v_max_f32_e32 v14, v9, v9
	v_max3_f32 v12, v12, v19, v8
	v_max_f32_e32 v13, v14, v13
	v_max3_f32 v12, v12, v13, v11
	ds_bpermute_b32 v13, v85, v12
	s_waitcnt lgkmcnt(0)
	v_max_f32_e32 v13, v13, v13
	v_max_f32_e32 v12, v12, v13
	ds_bpermute_b32 v13, v86, v12
	s_waitcnt lgkmcnt(0)
	v_max_f32_e32 v13, v13, v13
	v_max_f32_e32 v12, v12, v13
	v_sub_f32_e32 v13, v44, v12
	v_mul_f32_e32 v13, 0x3e38aa3b, v13
	v_sub_f32_e32 v15, v45, v12
	v_exp_f32_e32 v13, v13
	v_mul_f32_e32 v15, 0x3e38aa3b, v15
	v_sub_f32_e32 v44, v46, v12
	v_exp_f32_e32 v15, v15
	v_mul_f32_e32 v44, 0x3e38aa3b, v44
	v_sub_f32_e32 v45, v47, v12
	v_exp_f32_e32 v44, v44
	v_mul_f32_e32 v45, 0x3e38aa3b, v45
	v_sub_f32_e32 v46, v48, v12
	v_exp_f32_e32 v45, v45
	v_mul_f32_e32 v46, 0x3e38aa3b, v46
	v_sub_f32_e32 v47, v49, v12
	v_add_f32_e32 v14, 0, v13
	v_exp_f32_e32 v46, v46
	v_mul_f32_e32 v47, 0x3e38aa3b, v47
	v_sub_f32_e32 v48, v50, v12
	v_add_f32_e32 v14, v15, v14
	v_exp_f32_e32 v47, v47
	v_mul_f32_e32 v48, 0x3e38aa3b, v48
	v_sub_f32_e32 v49, v51, v12
	v_add_f32_e32 v14, v44, v14
	v_exp_f32_e32 v48, v48
	v_mul_f32_e32 v49, 0x3e38aa3b, v49
	v_sub_f32_e32 v50, v56, v12
	v_add_f32_e32 v14, v45, v14
	v_exp_f32_e32 v49, v49
	v_mul_f32_e32 v50, 0x3e38aa3b, v50
	v_sub_f32_e32 v51, v57, v12
	v_add_f32_e32 v14, v46, v14
	v_exp_f32_e32 v50, v50
	v_mul_f32_e32 v51, 0x3e38aa3b, v51
	v_sub_f32_e32 v56, v58, v12
	v_add_f32_e32 v14, v47, v14
	v_exp_f32_e32 v51, v51
	v_mul_f32_e32 v56, 0x3e38aa3b, v56
	v_sub_f32_e32 v57, v59, v12
	v_add_f32_e32 v14, v48, v14
	v_exp_f32_e32 v56, v56
	v_mul_f32_e32 v57, 0x3e38aa3b, v57
	v_sub_f32_e32 v58, v72, v12
	v_add_f32_e32 v14, v49, v14
	v_exp_f32_e32 v57, v57
	v_mul_f32_e32 v58, 0x3e38aa3b, v58
	v_sub_f32_e32 v59, v73, v12
	v_add_f32_e32 v14, v50, v14
	v_exp_f32_e32 v58, v58
	v_mul_f32_e32 v59, 0x3e38aa3b, v59
	v_sub_f32_e32 v72, v74, v12
	v_add_f32_e32 v14, v51, v14
	v_exp_f32_e32 v59, v59
	v_mul_f32_e32 v72, 0x3e38aa3b, v72
	v_sub_f32_e32 v73, v75, v12
	v_add_f32_e32 v14, v56, v14
	v_exp_f32_e32 v72, v72
	v_mul_f32_e32 v73, 0x3e38aa3b, v73
	v_sub_f32_e32 v74, v102, v12
	v_add_f32_e32 v14, v57, v14
	v_exp_f32_e32 v73, v73
	v_mul_f32_e32 v74, 0x3e38aa3b, v74
	v_sub_f32_e32 v75, v103, v12
	v_add_f32_e32 v14, v58, v14
	v_exp_f32_e32 v74, v74
	v_mul_f32_e32 v75, 0x3e38aa3b, v75
	v_sub_f32_e32 v102, v104, v12
	v_add_f32_e32 v14, v59, v14
	v_exp_f32_e32 v75, v75
	v_mul_f32_e32 v102, 0x3e38aa3b, v102
	v_sub_f32_e32 v103, v105, v12
	v_add_f32_e32 v14, v72, v14
	v_exp_f32_e32 v102, v102
	v_mul_f32_e32 v103, 0x3e38aa3b, v103
	v_sub_f32_e32 v104, v106, v12
	v_add_f32_e32 v14, v73, v14
	v_exp_f32_e32 v103, v103
	v_mul_f32_e32 v104, 0x3e38aa3b, v104
	v_sub_f32_e32 v105, v107, v12
	v_add_f32_e32 v14, v74, v14
	v_exp_f32_e32 v104, v104
	v_mul_f32_e32 v105, 0x3e38aa3b, v105
	v_sub_f32_e32 v106, v108, v12
	v_add_f32_e32 v14, v75, v14
	v_exp_f32_e32 v105, v105
	v_mul_f32_e32 v106, 0x3e38aa3b, v106
	v_sub_f32_e32 v107, v109, v12
	v_add_f32_e32 v14, v102, v14
	v_exp_f32_e32 v106, v106
	v_mul_f32_e32 v107, 0x3e38aa3b, v107
	v_sub_f32_e32 v108, v110, v12
	v_add_f32_e32 v14, v103, v14
	v_exp_f32_e32 v107, v107
	v_mul_f32_e32 v108, 0x3e38aa3b, v108
	v_sub_f32_e32 v109, v111, v12
	v_add_f32_e32 v14, v104, v14
	v_exp_f32_e32 v108, v108
	v_mul_f32_e32 v109, 0x3e38aa3b, v109
	v_sub_f32_e32 v110, v112, v12
	v_add_f32_e32 v14, v105, v14
	v_exp_f32_e32 v109, v109
	v_mul_f32_e32 v110, 0x3e38aa3b, v110
	v_sub_f32_e32 v111, v113, v12
	v_add_f32_e32 v14, v106, v14
	v_exp_f32_e32 v110, v110
	v_mul_f32_e32 v111, 0x3e38aa3b, v111
	v_sub_f32_e32 v112, v114, v12
	v_add_f32_e32 v14, v107, v14
	v_exp_f32_e32 v111, v111
	v_mul_f32_e32 v112, 0x3e38aa3b, v112
	v_sub_f32_e32 v113, v115, v12
	v_add_f32_e32 v14, v108, v14
	v_exp_f32_e32 v112, v112
	v_mul_f32_e32 v113, 0x3e38aa3b, v113
	v_sub_f32_e32 v114, v116, v12
	v_add_f32_e32 v14, v109, v14
	v_exp_f32_e32 v113, v113
	v_mul_f32_e32 v114, 0x3e38aa3b, v114
	v_sub_f32_e32 v115, v117, v12
	v_add_f32_e32 v14, v110, v14
	v_exp_f32_e32 v114, v114
	v_mul_f32_e32 v115, 0x3e38aa3b, v115
	v_sub_f32_e32 v40, v40, v12
	v_add_f32_e32 v14, v111, v14
	v_exp_f32_e32 v115, v115
	v_mul_f32_e32 v40, 0x3e38aa3b, v40
	v_sub_f32_e32 v41, v41, v12
	v_add_f32_e32 v14, v112, v14
	v_exp_f32_e32 v40, v40
	v_mul_f32_e32 v41, 0x3e38aa3b, v41
	v_sub_f32_e32 v42, v42, v12
	v_add_f32_e32 v14, v113, v14
	v_exp_f32_e32 v41, v41
	v_mul_f32_e32 v42, 0x3e38aa3b, v42
	v_sub_f32_e32 v43, v43, v12
	v_add_f32_e32 v14, v114, v14
	v_exp_f32_e32 v42, v42
	v_mul_f32_e32 v43, 0x3e38aa3b, v43
	v_sub_f32_e32 v36, v36, v12
	v_add_f32_e32 v14, v115, v14
	v_exp_f32_e32 v43, v43
	v_mul_f32_e32 v36, 0x3e38aa3b, v36
	v_sub_f32_e32 v37, v37, v12
	v_add_f32_e32 v14, v40, v14
	v_exp_f32_e32 v36, v36
	v_mul_f32_e32 v37, 0x3e38aa3b, v37
	v_sub_f32_e32 v38, v38, v12
	v_add_f32_e32 v14, v41, v14
	v_exp_f32_e32 v37, v37
	v_mul_f32_e32 v38, 0x3e38aa3b, v38
	v_sub_f32_e32 v39, v39, v12
	v_add_f32_e32 v14, v42, v14
	v_exp_f32_e32 v38, v38
	v_mul_f32_e32 v39, 0x3e38aa3b, v39
	v_sub_f32_e32 v32, v32, v12
	v_add_f32_e32 v14, v43, v14
	v_exp_f32_e32 v39, v39
	v_mul_f32_e32 v32, 0x3e38aa3b, v32
	v_sub_f32_e32 v33, v33, v12
	v_sub_f32_e32 v28, v28, v12
	v_add_f32_e32 v14, v36, v14
	v_exp_f32_e32 v32, v32
	v_mul_f32_e32 v33, 0x3e38aa3b, v33
	v_sub_f32_e32 v34, v34, v12
	v_mul_f32_e32 v28, 0x3e38aa3b, v28
	v_add_f32_e32 v14, v37, v14
	v_exp_f32_e32 v33, v33
	v_mul_f32_e32 v34, 0x3e38aa3b, v34
	v_sub_f32_e32 v35, v35, v12
	v_exp_f32_e32 v116, v28
	v_sub_f32_e32 v28, v29, v12
	v_add_f32_e32 v14, v38, v14
	v_exp_f32_e32 v34, v34
	v_mul_f32_e32 v35, 0x3e38aa3b, v35
	v_mul_f32_e32 v28, 0x3e38aa3b, v28
	v_add_f32_e32 v14, v39, v14
	v_exp_f32_e32 v35, v35
	v_exp_f32_e32 v117, v28
	v_sub_f32_e32 v28, v30, v12
	v_sub_f32_e32 v24, v24, v12
	v_add_f32_e32 v14, v32, v14
	v_mul_f32_e32 v28, 0x3e38aa3b, v28
	v_mul_f32_e32 v24, 0x3e38aa3b, v24
	v_add_f32_e32 v14, v33, v14
	v_exp_f32_e32 v118, v28
	v_sub_f32_e32 v28, v31, v12
	v_exp_f32_e32 v120, v24
	v_sub_f32_e32 v24, v25, v12
	v_add_f32_e32 v14, v34, v14
	v_mul_f32_e32 v28, 0x3e38aa3b, v28
	v_mul_f32_e32 v24, 0x3e38aa3b, v24
	v_add_f32_e32 v14, v35, v14
	v_exp_f32_e32 v119, v28
	v_exp_f32_e32 v121, v24
	v_sub_f32_e32 v24, v26, v12
	v_sub_f32_e32 v20, v20, v12
	v_add_f32_e32 v14, v116, v14
	v_mul_f32_e32 v24, 0x3e38aa3b, v24
	v_mul_f32_e32 v20, 0x3e38aa3b, v20
	v_add_f32_e32 v14, v117, v14
	v_exp_f32_e32 v122, v24
	v_sub_f32_e32 v24, v27, v12
	v_exp_f32_e32 v124, v20
	v_sub_f32_e32 v20, v21, v12
	v_add_f32_e32 v14, v118, v14
	v_mul_f32_e32 v24, 0x3e38aa3b, v24
	v_mul_f32_e32 v20, 0x3e38aa3b, v20
	v_add_f32_e32 v14, v119, v14
	v_exp_f32_e32 v123, v24
	v_exp_f32_e32 v125, v20
	v_sub_f32_e32 v20, v22, v12
	v_sub_f32_e32 v16, v16, v12
	v_add_f32_e32 v14, v120, v14
	v_mul_f32_e32 v20, 0x3e38aa3b, v20
	v_mul_f32_e32 v16, 0x3e38aa3b, v16
	v_add_f32_e32 v14, v121, v14
	v_exp_f32_e32 v126, v20
	v_sub_f32_e32 v20, v23, v12
	v_exp_f32_e32 v128, v16
	v_sub_f32_e32 v16, v17, v12
	v_add_f32_e32 v14, v122, v14
	v_mul_f32_e32 v20, 0x3e38aa3b, v20
	v_mul_f32_e32 v16, 0x3e38aa3b, v16
	v_add_f32_e32 v14, v123, v14
	v_exp_f32_e32 v127, v20
	v_exp_f32_e32 v129, v16
	v_sub_f32_e32 v16, v18, v12
	v_add_f32_e32 v14, v124, v14
	v_mul_f32_e32 v16, 0x3e38aa3b, v16
	v_add_f32_e32 v14, v125, v14
	v_exp_f32_e32 v130, v16
	v_sub_f32_e32 v16, v19, v12
	v_sub_f32_e32 v9, v9, v12
	v_add_f32_e32 v14, v126, v14
	v_mul_f32_e32 v16, 0x3e38aa3b, v16
	v_sub_f32_e32 v8, v8, v12
	v_mul_f32_e32 v9, 0x3e38aa3b, v9
	v_add_f32_e32 v14, v127, v14
	v_exp_f32_e32 v131, v16
	v_mul_f32_e32 v8, 0x3e38aa3b, v8
	v_exp_f32_e32 v133, v9
	v_sub_f32_e32 v9, v10, v12
	v_add_f32_e32 v14, v128, v14
	v_exp_f32_e32 v132, v8
	v_mul_f32_e32 v9, 0x3e38aa3b, v9
	v_add_f32_e32 v14, v129, v14
	v_exp_f32_e32 v134, v9
	v_sub_f32_e32 v9, v11, v12
	v_add_f32_e32 v14, v130, v14
	v_mul_f32_e32 v9, 0x3e38aa3b, v9
	v_add_f32_e32 v14, v131, v14
	v_exp_f32_e32 v135, v9
	v_add_f32_e32 v8, v132, v14
	v_add_f32_e32 v8, v133, v8
	v_add_f32_e32 v8, v134, v8
	v_add_f32_e32 v8, v135, v8
	ds_bpermute_b32 v9, v85, v8
	s_waitcnt lgkmcnt(0)
	v_add_f32_e32 v136, v8, v9
	v_cvt_pk_bf16_f32 v8, v13, v15
	v_cvt_pk_bf16_f32 v9, v44, v45
	v_cvt_pk_bf16_f32 v10, v46, v47
	v_cvt_pk_bf16_f32 v11, v48, v49
	ds_read2_b64 v[12:15], v52 offset1:4
	ds_read2_b64 v[16:19], v53 offset0:32 offset1:36
	ds_read2_b64 v[20:23], v54 offset0:64 offset1:68
	ds_read2_b64 v[24:27], v55 offset1:4
	s_waitcnt lgkmcnt(3)
	v_mfma_f32_16x16x32_bf16 v[12:15], v[12:15], v[8:11], 0
	ds_bpermute_b32 v137, v86, v136
	s_waitcnt lgkmcnt(3)
	v_mfma_f32_16x16x32_bf16 v[16:19], v[16:19], v[8:11], 0
	s_waitcnt lgkmcnt(2)
	v_mfma_f32_16x16x32_bf16 v[20:23], v[20:23], v[8:11], 0
	s_waitcnt lgkmcnt(1)
	v_mfma_f32_16x16x32_bf16 v[8:11], v[24:27], v[8:11], 0
	v_cvt_pk_bf16_f32 v24, v50, v51
	v_cvt_pk_bf16_f32 v25, v56, v57
	v_cvt_pk_bf16_f32 v26, v58, v59
	v_cvt_pk_bf16_f32 v27, v72, v73
	ds_read2_b64 v[28:31], v52 offset0:8 offset1:12
	s_waitcnt lgkmcnt(0)
	v_mfma_f32_16x16x32_bf16 v[12:15], v[28:31], v[24:27], v[12:15]
	ds_read2_b64 v[28:31], v53 offset0:40 offset1:44
	s_waitcnt lgkmcnt(0)
	v_mfma_f32_16x16x32_bf16 v[16:19], v[28:31], v[24:27], v[16:19]
	ds_read2_b64 v[28:31], v54 offset0:72 offset1:76
	s_waitcnt lgkmcnt(0)
	v_mfma_f32_16x16x32_bf16 v[20:23], v[28:31], v[24:27], v[20:23]
	ds_read2_b64 v[28:31], v55 offset0:8 offset1:12
	s_waitcnt lgkmcnt(0)
	v_mfma_f32_16x16x32_bf16 v[8:11], v[28:31], v[24:27], v[8:11]
	v_cvt_pk_bf16_f32 v24, v74, v75
	v_cvt_pk_bf16_f32 v25, v102, v103
	v_cvt_pk_bf16_f32 v26, v104, v105
	v_cvt_pk_bf16_f32 v27, v106, v107
	ds_read2_b64 v[28:31], v52 offset0:16 offset1:20
	s_waitcnt lgkmcnt(0)
	v_mfma_f32_16x16x32_bf16 v[12:15], v[28:31], v[24:27], v[12:15]
	ds_read2_b64 v[28:31], v53 offset0:48 offset1:52
	s_waitcnt lgkmcnt(0)
	v_mfma_f32_16x16x32_bf16 v[16:19], v[28:31], v[24:27], v[16:19]
	ds_read2_b64 v[28:31], v54 offset0:80 offset1:84
	s_waitcnt lgkmcnt(0)
	v_mfma_f32_16x16x32_bf16 v[20:23], v[28:31], v[24:27], v[20:23]
	ds_read2_b64 v[28:31], v55 offset0:16 offset1:20
	s_waitcnt lgkmcnt(0)
	v_mfma_f32_16x16x32_bf16 v[8:11], v[28:31], v[24:27], v[8:11]
	v_cvt_pk_bf16_f32 v24, v108, v109
	v_cvt_pk_bf16_f32 v25, v110, v111
	v_cvt_pk_bf16_f32 v26, v112, v113
	v_cvt_pk_bf16_f32 v27, v114, v115
	ds_read2_b64 v[28:31], v52 offset0:24 offset1:28
	s_waitcnt lgkmcnt(0)
	v_mfma_f32_16x16x32_bf16 v[12:15], v[28:31], v[24:27], v[12:15]
	ds_read2_b64 v[28:31], v53 offset0:56 offset1:60
	s_waitcnt lgkmcnt(0)
	v_mfma_f32_16x16x32_bf16 v[16:19], v[28:31], v[24:27], v[16:19]
	ds_read2_b64 v[28:31], v54 offset0:88 offset1:92
	s_waitcnt lgkmcnt(0)
	v_mfma_f32_16x16x32_bf16 v[20:23], v[28:31], v[24:27], v[20:23]
	ds_read2_b64 v[28:31], v55 offset0:24 offset1:28
	s_waitcnt lgkmcnt(0)
	v_mfma_f32_16x16x32_bf16 v[8:11], v[28:31], v[24:27], v[8:11]
	v_cvt_pk_bf16_f32 v24, v40, v41
	v_cvt_pk_bf16_f32 v25, v42, v43
	v_cvt_pk_bf16_f32 v26, v36, v37
	v_cvt_pk_bf16_f32 v27, v38, v39
	ds_read2_b64 v[28:31], v52 offset0:32 offset1:36
	s_waitcnt lgkmcnt(0)
	v_mfma_f32_16x16x32_bf16 v[12:15], v[28:31], v[24:27], v[12:15]
	ds_read2_b64 v[28:31], v53 offset0:64 offset1:68
	s_waitcnt lgkmcnt(0)
	v_mfma_f32_16x16x32_bf16 v[16:19], v[28:31], v[24:27], v[16:19]
	ds_read2_b64 v[28:31], v54 offset0:96 offset1:100
	s_waitcnt lgkmcnt(0)
	v_mfma_f32_16x16x32_bf16 v[20:23], v[28:31], v[24:27], v[20:23]
	ds_read2_b64 v[28:31], v55 offset0:32 offset1:36
	s_waitcnt lgkmcnt(0)
	v_mfma_f32_16x16x32_bf16 v[8:11], v[28:31], v[24:27], v[8:11]
	v_cvt_pk_bf16_f32 v24, v32, v33
	v_cvt_pk_bf16_f32 v25, v34, v35
	v_cvt_pk_bf16_f32 v26, v116, v117
	v_cvt_pk_bf16_f32 v27, v118, v119
	ds_read2_b64 v[28:31], v52 offset0:40 offset1:44
	s_waitcnt lgkmcnt(0)
	v_mfma_f32_16x16x32_bf16 v[12:15], v[28:31], v[24:27], v[12:15]
	ds_read2_b64 v[28:31], v53 offset0:72 offset1:76
	s_waitcnt lgkmcnt(0)
	v_mfma_f32_16x16x32_bf16 v[16:19], v[28:31], v[24:27], v[16:19]
	ds_read2_b64 v[28:31], v54 offset0:104 offset1:108
	s_waitcnt lgkmcnt(0)
	v_mfma_f32_16x16x32_bf16 v[20:23], v[28:31], v[24:27], v[20:23]
	ds_read2_b64 v[28:31], v55 offset0:40 offset1:44
	s_waitcnt lgkmcnt(0)
	v_mfma_f32_16x16x32_bf16 v[8:11], v[28:31], v[24:27], v[8:11]
	v_cvt_pk_bf16_f32 v24, v120, v121
	v_cvt_pk_bf16_f32 v25, v122, v123
	v_cvt_pk_bf16_f32 v26, v124, v125
	v_cvt_pk_bf16_f32 v27, v126, v127
	ds_read2_b64 v[28:31], v52 offset0:48 offset1:52
	s_waitcnt lgkmcnt(0)
	v_mfma_f32_16x16x32_bf16 v[12:15], v[28:31], v[24:27], v[12:15]
	ds_read2_b64 v[28:31], v53 offset0:80 offset1:84
	s_waitcnt lgkmcnt(0)
	v_mfma_f32_16x16x32_bf16 v[16:19], v[28:31], v[24:27], v[16:19]
	ds_read2_b64 v[28:31], v54 offset0:112 offset1:116
	s_waitcnt lgkmcnt(0)
	v_mfma_f32_16x16x32_bf16 v[28:31], v[28:31], v[24:27], v[20:23]
	s_nop 2
	ds_read2_b64 v[20:23], v55 offset0:48 offset1:52
	s_waitcnt lgkmcnt(0)
	v_mfma_f32_16x16x32_bf16 v[8:11], v[20:23], v[24:27], v[8:11]
	v_cvt_pk_bf16_f32 v24, v128, v129
	v_cvt_pk_bf16_f32 v25, v130, v131
	v_cvt_pk_bf16_f32 v26, v132, v133
	v_cvt_pk_bf16_f32 v27, v134, v135
	ds_read2_b64 v[20:23], v52 offset0:56 offset1:60
	s_waitcnt lgkmcnt(0)
	v_mfma_f32_16x16x32_bf16 v[20:23], v[20:23], v[24:27], v[12:15]
	s_nop 2
	ds_read2_b64 v[12:15], v53 offset0:88 offset1:92
	s_waitcnt lgkmcnt(0)
	v_mfma_f32_16x16x32_bf16 v[16:19], v[12:15], v[24:27], v[16:19]
	ds_read2_b64 v[12:15], v54 offset0:120 offset1:124
	s_waitcnt lgkmcnt(0)
	v_mfma_f32_16x16x32_bf16 v[12:15], v[12:15], v[24:27], v[28:31]
	s_nop 2
	ds_read2_b64 v[28:31], v55 offset0:56 offset1:60
	s_waitcnt lgkmcnt(0)
	v_mfma_f32_16x16x32_bf16 v[8:11], v[28:31], v[24:27], v[8:11]
	v_add_f32_e32 v24, v136, v137
	v_div_scale_f32 v25, s[8:9], v24, v24, 1.0
	v_rcp_f32_e32 v26, v25
	s_nop 0
	v_fma_f32 v27, -v25, v26, 1.0
	v_fmac_f32_e32 v26, v27, v26
	v_div_scale_f32 v27, vcc, 1.0, v24, 1.0
	v_mul_f32_e32 v28, v27, v26
	v_fma_f32 v29, -v25, v28, v27
	v_fmac_f32_e32 v28, v29, v26
	v_fma_f32 v25, -v25, v28, v27
	v_div_fmas_f32 v25, v25, v26, v28
	v_div_fixup_f32 v26, v25, v24, 1.0
	v_lshlrev_b64 v[24:25], 11, v[70:71]
	v_lshl_add_u64 v[24:25], s[66:67], 0, v[24:25]
	v_lshl_add_u64 v[24:25], v[24:25], 0, s[70:71]
	v_mul_f32_e32 v20, v26, v20
	v_mul_f32_e32 v21, v26, v21
	v_lshl_add_u64 v[24:25], v[24:25], 0, v[184:185]
	v_cvt_pk_bf16_f32 v20, v20, v21
	v_mul_f32_e32 v21, v26, v22
	v_mul_f32_e32 v16, v26, v16
	v_mul_f32_e32 v17, v26, v17
	v_mul_f32_e32 v22, v26, v23
	v_cvt_pk_bf16_f32 v21, v21, v22
	global_store_dwordx2 v[24:25], v[20:21], off offset:1536
	v_cvt_pk_bf16_f32 v16, v16, v17
	v_mul_f32_e32 v17, v26, v18
	v_mul_f32_e32 v12, v26, v12
	v_mul_f32_e32 v13, v26, v13
	v_mul_f32_e32 v18, v26, v19
	v_cvt_pk_bf16_f32 v17, v17, v18
	global_store_dwordx2 v[24:25], v[16:17], off offset:1568
	v_cvt_pk_bf16_f32 v12, v12, v13
	v_mul_f32_e32 v13, v26, v14
	v_mul_f32_e32 v8, v26, v8
	v_mul_f32_e32 v9, v26, v9
	v_mul_f32_e32 v14, v26, v15
	v_cvt_pk_bf16_f32 v13, v13, v14
	global_store_dwordx2 v[24:25], v[12:13], off offset:1600
	v_cvt_pk_bf16_f32 v8, v8, v9
	v_mul_f32_e32 v9, v26, v10
	v_mul_f32_e32 v10, v26, v11
	v_cvt_pk_bf16_f32 v9, v9, v10
	global_store_dwordx2 v[24:25], v[8:9], off offset:1632
	ds_read_b128 v[8:11], v95
	ds_read_b128 v[12:15], v95 offset:64
	s_waitcnt lgkmcnt(1)
	v_mfma_f32_16x16x32_bf16 v[8:11], v[8:11], v[0:3], 0
	s_waitcnt lgkmcnt(0)
	v_mfma_f32_16x16x32_bf16 v[36:39], v[12:15], v[4:7], v[8:11]
	s_nop 5
	ds_read_b128 v[8:11], v95 offset:2304
	ds_read_b128 v[12:15], v95 offset:2368
	s_waitcnt lgkmcnt(1)
	v_mfma_f32_16x16x32_bf16 v[8:11], v[8:11], v[0:3], 0
	s_waitcnt lgkmcnt(0)
	v_mfma_f32_16x16x32_bf16 v[40:43], v[12:15], v[4:7], v[8:11]
	s_nop 5
	ds_read_b128 v[8:11], v95 offset:4608
	ds_read_b128 v[12:15], v95 offset:4672
	s_waitcnt lgkmcnt(1)
	v_mfma_f32_16x16x32_bf16 v[8:11], v[8:11], v[0:3], 0
	s_waitcnt lgkmcnt(0)
	v_mfma_f32_16x16x32_bf16 v[44:47], v[12:15], v[4:7], v[8:11]
	s_nop 5
	ds_read_b128 v[8:11], v96
	ds_read_b128 v[12:15], v96 offset:64
	s_waitcnt lgkmcnt(1)
	v_mfma_f32_16x16x32_bf16 v[8:11], v[8:11], v[0:3], 0
	s_waitcnt lgkmcnt(0)
	v_mfma_f32_16x16x32_bf16 v[48:51], v[12:15], v[4:7], v[8:11]
	s_nop 5
	ds_read_b128 v[8:11], v95 offset:9216
	ds_read_b128 v[12:15], v95 offset:9280
	s_waitcnt lgkmcnt(1)
	v_mfma_f32_16x16x32_bf16 v[8:11], v[8:11], v[0:3], 0
	s_waitcnt lgkmcnt(0)
	v_mfma_f32_16x16x32_bf16 v[56:59], v[12:15], v[4:7], v[8:11]
	s_nop 5
	ds_read_b128 v[8:11], v95 offset:11520
	ds_read_b128 v[12:15], v95 offset:11584
	s_waitcnt lgkmcnt(1)
	v_mfma_f32_16x16x32_bf16 v[8:11], v[8:11], v[0:3], 0
	s_waitcnt lgkmcnt(0)
	v_mfma_f32_16x16x32_bf16 v[70:73], v[12:15], v[4:7], v[8:11]
	s_nop 5
	ds_read_b128 v[8:11], v95 offset:13824
	ds_read_b128 v[12:15], v95 offset:13888
	s_waitcnt lgkmcnt(1)
	v_mfma_f32_16x16x32_bf16 v[8:11], v[8:11], v[0:3], 0
	s_waitcnt lgkmcnt(0)
	v_mfma_f32_16x16x32_bf16 v[102:105], v[12:15], v[4:7], v[8:11]
	s_nop 5
	ds_read_b128 v[8:11], v97
	ds_read_b128 v[12:15], v97 offset:64
	s_waitcnt lgkmcnt(1)
	v_mfma_f32_16x16x32_bf16 v[8:11], v[8:11], v[0:3], 0
	s_waitcnt lgkmcnt(0)
	v_mfma_f32_16x16x32_bf16 v[106:109], v[12:15], v[4:7], v[8:11]
	s_nop 5
	ds_read_b128 v[8:11], v95 offset:18432
	ds_read_b128 v[12:15], v95 offset:18496
	s_waitcnt lgkmcnt(1)
	v_mfma_f32_16x16x32_bf16 v[8:11], v[8:11], v[0:3], 0
	s_waitcnt lgkmcnt(0)
	v_mfma_f32_16x16x32_bf16 v[32:35], v[12:15], v[4:7], v[8:11]
	s_nop 5
	ds_read_b128 v[8:11], v95 offset:20736
	ds_read_b128 v[12:15], v95 offset:20800
	s_waitcnt lgkmcnt(1)
	v_mfma_f32_16x16x32_bf16 v[8:11], v[8:11], v[0:3], 0
	s_waitcnt lgkmcnt(0)
	v_mfma_f32_16x16x32_bf16 v[28:31], v[12:15], v[4:7], v[8:11]
	s_nop 5
	ds_read_b128 v[8:11], v95 offset:23040
	ds_read_b128 v[12:15], v95 offset:23104
	s_waitcnt lgkmcnt(1)
	v_mfma_f32_16x16x32_bf16 v[8:11], v[8:11], v[0:3], 0
	s_waitcnt lgkmcnt(0)
	v_mfma_f32_16x16x32_bf16 v[24:27], v[12:15], v[4:7], v[8:11]
	s_nop 5
	ds_read_b128 v[8:11], v98
	ds_read_b128 v[12:15], v98 offset:64
	s_waitcnt lgkmcnt(1)
	v_mfma_f32_16x16x32_bf16 v[8:11], v[8:11], v[0:3], 0
	s_waitcnt lgkmcnt(0)
	v_mfma_f32_16x16x32_bf16 v[20:23], v[12:15], v[4:7], v[8:11]
	s_nop 5
	ds_read_b128 v[8:11], v95 offset:27648
	ds_read_b128 v[12:15], v95 offset:27712
	s_waitcnt lgkmcnt(1)
	v_mfma_f32_16x16x32_bf16 v[8:11], v[8:11], v[0:3], 0
	s_waitcnt lgkmcnt(0)
	v_mfma_f32_16x16x32_bf16 v[16:19], v[12:15], v[4:7], v[8:11]
	s_nop 5
	ds_read_b128 v[8:11], v95 offset:29952
	ds_read_b128 v[12:15], v95 offset:30016
	s_waitcnt lgkmcnt(1)
	v_mfma_f32_16x16x32_bf16 v[8:11], v[8:11], v[0:3], 0
	s_waitcnt lgkmcnt(0)
	v_mfma_f32_16x16x32_bf16 v[12:15], v[12:15], v[4:7], v[8:11]
	s_nop 5
	ds_read_b128 v[8:11], v95 offset:32256
	ds_read_b128 v[110:113], v95 offset:32320
	s_waitcnt lgkmcnt(1)
	v_mfma_f32_16x16x32_bf16 v[8:11], v[8:11], v[0:3], 0
	s_waitcnt lgkmcnt(0)
	v_mfma_f32_16x16x32_bf16 v[8:11], v[110:113], v[4:7], v[8:11]
	ds_read_b128 v[110:113], v99
	ds_read_b128 v[114:117], v99 offset:64
	s_waitcnt lgkmcnt(1)
	v_mfma_f32_16x16x32_bf16 v[0:3], v[110:113], v[0:3], 0
	s_waitcnt lgkmcnt(0)
	v_mfma_f32_16x16x32_bf16 v[0:3], v[114:117], v[4:7], v[0:3]
	v_max3_f32 v4, v36, v37, v38
	v_max_f32_e32 v5, v42, v42
	v_max_f32_e32 v6, v41, v41
	v_max3_f32 v4, v4, v39, v40
	v_max_f32_e32 v5, v6, v5
	v_max3_f32 v4, v4, v5, v43
	v_max_f32_e32 v5, v46, v46
	v_max_f32_e32 v6, v45, v45
	v_max_f32_e32 v5, v6, v5
	v_max3_f32 v4, v4, v44, v5
	v_max_f32_e32 v5, v50, v50
	v_max_f32_e32 v6, v49, v49
	v_max3_f32 v4, v4, v47, v48
	v_max_f32_e32 v5, v6, v5
	v_max3_f32 v4, v4, v5, v51
	v_max_f32_e32 v5, v58, v58
	v_max_f32_e32 v6, v57, v57
	v_max_f32_e32 v5, v6, v5
	v_max3_f32 v4, v4, v56, v5
	v_max_f32_e32 v5, v72, v72
	v_max_f32_e32 v6, v71, v71
	v_max3_f32 v4, v4, v59, v70
	v_max_f32_e32 v5, v6, v5
	v_max3_f32 v4, v4, v5, v73
	v_max_f32_e32 v5, v104, v104
	v_max_f32_e32 v6, v103, v103
	v_max_f32_e32 v5, v6, v5
	v_max3_f32 v4, v4, v102, v5
	v_max_f32_e32 v5, v108, v108
	v_max_f32_e32 v6, v107, v107
	v_max3_f32 v4, v4, v105, v106
	v_max_f32_e32 v5, v6, v5
	v_max3_f32 v4, v4, v5, v109
	v_max_f32_e32 v5, v34, v34
	v_max_f32_e32 v6, v33, v33
	v_max_f32_e32 v5, v6, v5
	v_max3_f32 v4, v4, v32, v5
	v_max_f32_e32 v5, v30, v30
	v_max_f32_e32 v6, v29, v29
	v_max3_f32 v4, v4, v35, v28
	v_max_f32_e32 v5, v6, v5
	v_max3_f32 v4, v4, v5, v31
	v_max_f32_e32 v5, v26, v26
	v_max_f32_e32 v6, v25, v25
	v_max_f32_e32 v5, v6, v5
	v_max3_f32 v4, v4, v24, v5
	v_max_f32_e32 v5, v22, v22
	v_max_f32_e32 v6, v21, v21
	v_max3_f32 v4, v4, v27, v20
	v_max_f32_e32 v5, v6, v5
	v_max3_f32 v4, v4, v5, v23
	v_max_f32_e32 v5, v18, v18
	v_max_f32_e32 v6, v17, v17
	v_max_f32_e32 v5, v6, v5
	v_max3_f32 v4, v4, v16, v5
	v_max_f32_e32 v5, v14, v14
	v_max_f32_e32 v6, v13, v13
	v_max3_f32 v4, v4, v19, v12
	v_max_f32_e32 v5, v6, v5
	v_max3_f32 v4, v4, v5, v15
	v_max_f32_e32 v5, v10, v10
	v_max_f32_e32 v6, v9, v9
	v_max_f32_e32 v5, v6, v5
	v_max3_f32 v4, v4, v8, v5
	v_max_f32_e32 v5, v2, v2
	v_max_f32_e32 v6, v1, v1
	v_max3_f32 v4, v4, v11, v0
	v_max_f32_e32 v5, v6, v5
	v_max3_f32 v4, v4, v5, v3
	ds_bpermute_b32 v5, v85, v4
	s_waitcnt lgkmcnt(0)
	v_max_f32_e32 v5, v5, v5
	v_max_f32_e32 v4, v4, v5
	ds_bpermute_b32 v5, v86, v4
	s_waitcnt lgkmcnt(0)
	v_max_f32_e32 v5, v5, v5
	v_max_f32_e32 v4, v4, v5
	v_sub_f32_e32 v5, v36, v4
	v_mul_f32_e32 v5, 0x3e38aa3b, v5
	v_sub_f32_e32 v7, v37, v4
	v_exp_f32_e32 v5, v5
	v_mul_f32_e32 v7, 0x3e38aa3b, v7
	v_sub_f32_e32 v36, v38, v4
	v_exp_f32_e32 v7, v7
	v_mul_f32_e32 v36, 0x3e38aa3b, v36
	v_sub_f32_e32 v37, v39, v4
	v_exp_f32_e32 v36, v36
	v_mul_f32_e32 v37, 0x3e38aa3b, v37
	v_sub_f32_e32 v38, v40, v4
	v_exp_f32_e32 v37, v37
	v_mul_f32_e32 v38, 0x3e38aa3b, v38
	v_sub_f32_e32 v39, v41, v4
	v_add_f32_e32 v6, 0, v5
	v_exp_f32_e32 v38, v38
	v_mul_f32_e32 v39, 0x3e38aa3b, v39
	v_sub_f32_e32 v40, v42, v4
	v_add_f32_e32 v6, v7, v6
	v_exp_f32_e32 v39, v39
	v_mul_f32_e32 v40, 0x3e38aa3b, v40
	v_sub_f32_e32 v41, v43, v4
	v_add_f32_e32 v6, v36, v6
	v_exp_f32_e32 v40, v40
	v_mul_f32_e32 v41, 0x3e38aa3b, v41
	v_sub_f32_e32 v42, v44, v4
	v_add_f32_e32 v6, v37, v6
	v_exp_f32_e32 v41, v41
	v_mul_f32_e32 v42, 0x3e38aa3b, v42
	v_sub_f32_e32 v43, v45, v4
	v_add_f32_e32 v6, v38, v6
	v_exp_f32_e32 v42, v42
	v_mul_f32_e32 v43, 0x3e38aa3b, v43
	v_sub_f32_e32 v44, v46, v4
	v_add_f32_e32 v6, v39, v6
	v_exp_f32_e32 v43, v43
	v_mul_f32_e32 v44, 0x3e38aa3b, v44
	v_sub_f32_e32 v45, v47, v4
	v_add_f32_e32 v6, v40, v6
	v_exp_f32_e32 v44, v44
	v_mul_f32_e32 v45, 0x3e38aa3b, v45
	v_sub_f32_e32 v46, v48, v4
	v_add_f32_e32 v6, v41, v6
	v_exp_f32_e32 v45, v45
	v_mul_f32_e32 v46, 0x3e38aa3b, v46
	v_sub_f32_e32 v47, v49, v4
	v_add_f32_e32 v6, v42, v6
	v_exp_f32_e32 v46, v46
	v_mul_f32_e32 v47, 0x3e38aa3b, v47
	v_sub_f32_e32 v48, v50, v4
	v_add_f32_e32 v6, v43, v6
	v_exp_f32_e32 v47, v47
	v_mul_f32_e32 v48, 0x3e38aa3b, v48
	v_sub_f32_e32 v49, v51, v4
	v_add_f32_e32 v6, v44, v6
	v_exp_f32_e32 v48, v48
	v_mul_f32_e32 v49, 0x3e38aa3b, v49
	v_sub_f32_e32 v50, v56, v4
	v_add_f32_e32 v6, v45, v6
	v_exp_f32_e32 v49, v49
	v_mul_f32_e32 v50, 0x3e38aa3b, v50
	v_sub_f32_e32 v51, v57, v4
	v_add_f32_e32 v6, v46, v6
	v_exp_f32_e32 v50, v50
	v_mul_f32_e32 v51, 0x3e38aa3b, v51
	v_sub_f32_e32 v56, v58, v4
	v_add_f32_e32 v6, v47, v6
	v_exp_f32_e32 v51, v51
	v_mul_f32_e32 v56, 0x3e38aa3b, v56
	v_sub_f32_e32 v57, v59, v4
	v_add_f32_e32 v6, v48, v6
	v_exp_f32_e32 v56, v56
	v_mul_f32_e32 v57, 0x3e38aa3b, v57
	v_sub_f32_e32 v58, v70, v4
	v_add_f32_e32 v6, v49, v6
	v_exp_f32_e32 v57, v57
	v_mul_f32_e32 v58, 0x3e38aa3b, v58
	v_sub_f32_e32 v59, v71, v4
	v_add_f32_e32 v6, v50, v6
	v_exp_f32_e32 v58, v58
	v_mul_f32_e32 v59, 0x3e38aa3b, v59
	v_sub_f32_e32 v70, v72, v4
	v_add_f32_e32 v6, v51, v6
	v_exp_f32_e32 v59, v59
	v_mul_f32_e32 v70, 0x3e38aa3b, v70
	v_sub_f32_e32 v71, v73, v4
	v_add_f32_e32 v6, v56, v6
	v_exp_f32_e32 v70, v70
	v_mul_f32_e32 v71, 0x3e38aa3b, v71
	v_sub_f32_e32 v72, v102, v4
	v_add_f32_e32 v6, v57, v6
	v_exp_f32_e32 v71, v71
	v_mul_f32_e32 v72, 0x3e38aa3b, v72
	v_sub_f32_e32 v73, v103, v4
	v_add_f32_e32 v6, v58, v6
	v_exp_f32_e32 v72, v72
	v_mul_f32_e32 v73, 0x3e38aa3b, v73
	v_sub_f32_e32 v74, v104, v4
	v_add_f32_e32 v6, v59, v6
	v_exp_f32_e32 v73, v73
	v_mul_f32_e32 v74, 0x3e38aa3b, v74
	v_sub_f32_e32 v75, v105, v4
	v_add_f32_e32 v6, v70, v6
	v_exp_f32_e32 v74, v74
	v_mul_f32_e32 v75, 0x3e38aa3b, v75
	v_sub_f32_e32 v102, v106, v4
	v_add_f32_e32 v6, v71, v6
	v_exp_f32_e32 v75, v75
	v_mul_f32_e32 v102, 0x3e38aa3b, v102
	v_sub_f32_e32 v103, v107, v4
	v_add_f32_e32 v6, v72, v6
	v_exp_f32_e32 v102, v102
	v_mul_f32_e32 v103, 0x3e38aa3b, v103
	v_sub_f32_e32 v104, v108, v4
	v_add_f32_e32 v6, v73, v6
	v_exp_f32_e32 v103, v103
	v_mul_f32_e32 v104, 0x3e38aa3b, v104
	v_sub_f32_e32 v105, v109, v4
	v_add_f32_e32 v6, v74, v6
	v_exp_f32_e32 v104, v104
	v_mul_f32_e32 v105, 0x3e38aa3b, v105
	v_sub_f32_e32 v32, v32, v4
	v_add_f32_e32 v6, v75, v6
	v_exp_f32_e32 v105, v105
	v_mul_f32_e32 v32, 0x3e38aa3b, v32
	v_sub_f32_e32 v33, v33, v4
	v_add_f32_e32 v6, v102, v6
	v_exp_f32_e32 v32, v32
	v_mul_f32_e32 v33, 0x3e38aa3b, v33
	v_sub_f32_e32 v34, v34, v4
	v_add_f32_e32 v6, v103, v6
	v_exp_f32_e32 v33, v33
	v_mul_f32_e32 v34, 0x3e38aa3b, v34
	v_sub_f32_e32 v35, v35, v4
	v_add_f32_e32 v6, v104, v6
	v_exp_f32_e32 v34, v34
	v_mul_f32_e32 v35, 0x3e38aa3b, v35
	v_sub_f32_e32 v28, v28, v4
	v_add_f32_e32 v6, v105, v6
	v_exp_f32_e32 v35, v35
	v_mul_f32_e32 v28, 0x3e38aa3b, v28
	v_sub_f32_e32 v29, v29, v4
	v_add_f32_e32 v6, v32, v6
	v_exp_f32_e32 v28, v28
	v_mul_f32_e32 v29, 0x3e38aa3b, v29
	v_sub_f32_e32 v30, v30, v4
	v_add_f32_e32 v6, v33, v6
	v_exp_f32_e32 v29, v29
	v_mul_f32_e32 v30, 0x3e38aa3b, v30
	v_sub_f32_e32 v31, v31, v4
	v_add_f32_e32 v6, v34, v6
	v_exp_f32_e32 v30, v30
	v_mul_f32_e32 v31, 0x3e38aa3b, v31
	v_sub_f32_e32 v24, v24, v4
	v_add_f32_e32 v6, v35, v6
	v_exp_f32_e32 v31, v31
	v_mul_f32_e32 v24, 0x3e38aa3b, v24
	v_sub_f32_e32 v25, v25, v4
	v_sub_f32_e32 v20, v20, v4
	v_add_f32_e32 v6, v28, v6
	v_exp_f32_e32 v24, v24
	v_mul_f32_e32 v25, 0x3e38aa3b, v25
	v_sub_f32_e32 v26, v26, v4
	v_mul_f32_e32 v20, 0x3e38aa3b, v20
	v_add_f32_e32 v6, v29, v6
	v_exp_f32_e32 v25, v25
	v_mul_f32_e32 v26, 0x3e38aa3b, v26
	v_sub_f32_e32 v27, v27, v4
	v_exp_f32_e32 v106, v20
	v_sub_f32_e32 v20, v21, v4
	v_add_f32_e32 v6, v30, v6
	v_exp_f32_e32 v26, v26
	v_mul_f32_e32 v27, 0x3e38aa3b, v27
	v_mul_f32_e32 v20, 0x3e38aa3b, v20
	v_add_f32_e32 v6, v31, v6
	v_exp_f32_e32 v27, v27
	v_exp_f32_e32 v107, v20
	v_sub_f32_e32 v20, v22, v4
	v_sub_f32_e32 v16, v16, v4
	v_add_f32_e32 v6, v24, v6
	v_mul_f32_e32 v20, 0x3e38aa3b, v20
	v_mul_f32_e32 v16, 0x3e38aa3b, v16
	v_add_f32_e32 v6, v25, v6
	v_exp_f32_e32 v108, v20
	v_sub_f32_e32 v20, v23, v4
	v_exp_f32_e32 v110, v16
	v_sub_f32_e32 v16, v17, v4
	v_add_f32_e32 v6, v26, v6
	v_mul_f32_e32 v20, 0x3e38aa3b, v20
	v_mul_f32_e32 v16, 0x3e38aa3b, v16
	v_add_f32_e32 v6, v27, v6
	v_exp_f32_e32 v109, v20
	v_exp_f32_e32 v111, v16
	v_sub_f32_e32 v16, v18, v4
	v_sub_f32_e32 v12, v12, v4
	v_add_f32_e32 v6, v106, v6
	v_mul_f32_e32 v16, 0x3e38aa3b, v16
	v_mul_f32_e32 v12, 0x3e38aa3b, v12
	v_add_f32_e32 v6, v107, v6
	v_exp_f32_e32 v112, v16
	v_sub_f32_e32 v16, v19, v4
	v_exp_f32_e32 v114, v12
	v_sub_f32_e32 v12, v13, v4
	v_add_f32_e32 v6, v108, v6
	v_mul_f32_e32 v16, 0x3e38aa3b, v16
	v_mul_f32_e32 v12, 0x3e38aa3b, v12
	v_add_f32_e32 v6, v109, v6
	v_exp_f32_e32 v113, v16
	v_exp_f32_e32 v115, v12
	v_sub_f32_e32 v12, v14, v4
	v_sub_f32_e32 v8, v8, v4
	v_add_f32_e32 v6, v110, v6
	v_mul_f32_e32 v12, 0x3e38aa3b, v12
	v_mul_f32_e32 v8, 0x3e38aa3b, v8
	v_add_f32_e32 v6, v111, v6
	v_exp_f32_e32 v116, v12
	v_sub_f32_e32 v12, v15, v4
	v_exp_f32_e32 v118, v8
	v_sub_f32_e32 v8, v9, v4
	v_add_f32_e32 v6, v112, v6
	v_mul_f32_e32 v12, 0x3e38aa3b, v12
	v_mul_f32_e32 v8, 0x3e38aa3b, v8
	v_add_f32_e32 v6, v113, v6
	v_exp_f32_e32 v117, v12
	v_exp_f32_e32 v119, v8
	v_sub_f32_e32 v8, v10, v4
	v_add_f32_e32 v6, v114, v6
	v_mul_f32_e32 v8, 0x3e38aa3b, v8
	v_add_f32_e32 v6, v115, v6
	v_exp_f32_e32 v120, v8
	v_sub_f32_e32 v8, v11, v4
	v_sub_f32_e32 v1, v1, v4
	v_add_f32_e32 v6, v116, v6
	v_mul_f32_e32 v8, 0x3e38aa3b, v8
	v_sub_f32_e32 v0, v0, v4
	v_mul_f32_e32 v1, 0x3e38aa3b, v1
	v_add_f32_e32 v6, v117, v6
	v_exp_f32_e32 v121, v8
	v_mul_f32_e32 v0, 0x3e38aa3b, v0
	v_exp_f32_e32 v123, v1
	v_sub_f32_e32 v1, v2, v4
	v_add_f32_e32 v6, v118, v6
	v_exp_f32_e32 v122, v0
	v_mul_f32_e32 v1, 0x3e38aa3b, v1
	v_add_f32_e32 v6, v119, v6
	v_exp_f32_e32 v124, v1
	v_sub_f32_e32 v1, v3, v4
	v_add_f32_e32 v6, v120, v6
	v_mul_f32_e32 v1, 0x3e38aa3b, v1
	v_add_f32_e32 v6, v121, v6
	v_exp_f32_e32 v125, v1
	v_add_f32_e32 v0, v122, v6
	v_add_f32_e32 v0, v123, v0
	v_add_f32_e32 v0, v124, v0
	v_add_f32_e32 v0, v125, v0
	ds_bpermute_b32 v1, v85, v0
	s_waitcnt lgkmcnt(0)
	v_add_f32_e32 v126, v0, v1
	v_cvt_pk_bf16_f32 v0, v5, v7
	v_cvt_pk_bf16_f32 v1, v36, v37
	v_cvt_pk_bf16_f32 v2, v38, v39
	v_cvt_pk_bf16_f32 v3, v40, v41
	ds_read2_b64 v[4:7], v52 offset1:4
	ds_read2_b64 v[8:11], v53 offset0:32 offset1:36
	ds_read2_b64 v[12:15], v54 offset0:64 offset1:68
	ds_read2_b64 v[16:19], v55 offset1:4
	s_waitcnt lgkmcnt(3)
	v_mfma_f32_16x16x32_bf16 v[4:7], v[4:7], v[0:3], 0
	ds_bpermute_b32 v127, v86, v126
	s_waitcnt lgkmcnt(3)
	v_mfma_f32_16x16x32_bf16 v[8:11], v[8:11], v[0:3], 0
	s_waitcnt lgkmcnt(2)
	v_mfma_f32_16x16x32_bf16 v[12:15], v[12:15], v[0:3], 0
	s_waitcnt lgkmcnt(1)
	v_mfma_f32_16x16x32_bf16 v[0:3], v[16:19], v[0:3], 0
	v_cvt_pk_bf16_f32 v16, v42, v43
	v_cvt_pk_bf16_f32 v17, v44, v45
	v_cvt_pk_bf16_f32 v18, v46, v47
	v_cvt_pk_bf16_f32 v19, v48, v49
	ds_read2_b64 v[20:23], v52 offset0:8 offset1:12
	s_waitcnt lgkmcnt(0)
	v_mfma_f32_16x16x32_bf16 v[4:7], v[20:23], v[16:19], v[4:7]
	ds_read2_b64 v[20:23], v53 offset0:40 offset1:44
	s_waitcnt lgkmcnt(0)
	v_mfma_f32_16x16x32_bf16 v[8:11], v[20:23], v[16:19], v[8:11]
	ds_read2_b64 v[20:23], v54 offset0:72 offset1:76
	s_waitcnt lgkmcnt(0)
	v_mfma_f32_16x16x32_bf16 v[12:15], v[20:23], v[16:19], v[12:15]
	ds_read2_b64 v[20:23], v55 offset0:8 offset1:12
	s_waitcnt lgkmcnt(0)
	v_mfma_f32_16x16x32_bf16 v[0:3], v[20:23], v[16:19], v[0:3]
	v_cvt_pk_bf16_f32 v16, v50, v51
	v_cvt_pk_bf16_f32 v17, v56, v57
	v_cvt_pk_bf16_f32 v18, v58, v59
	v_cvt_pk_bf16_f32 v19, v70, v71
	ds_read2_b64 v[20:23], v52 offset0:16 offset1:20
	s_waitcnt lgkmcnt(0)
	v_mfma_f32_16x16x32_bf16 v[4:7], v[20:23], v[16:19], v[4:7]
	ds_read2_b64 v[20:23], v53 offset0:48 offset1:52
	s_waitcnt lgkmcnt(0)
	v_mfma_f32_16x16x32_bf16 v[8:11], v[20:23], v[16:19], v[8:11]
	ds_read2_b64 v[20:23], v54 offset0:80 offset1:84
	s_waitcnt lgkmcnt(0)
	v_mfma_f32_16x16x32_bf16 v[12:15], v[20:23], v[16:19], v[12:15]
	ds_read2_b64 v[20:23], v55 offset0:16 offset1:20
	s_waitcnt lgkmcnt(0)
	v_mfma_f32_16x16x32_bf16 v[0:3], v[20:23], v[16:19], v[0:3]
	v_cvt_pk_bf16_f32 v16, v72, v73
	v_cvt_pk_bf16_f32 v17, v74, v75
	v_cvt_pk_bf16_f32 v18, v102, v103
	v_cvt_pk_bf16_f32 v19, v104, v105
	ds_read2_b64 v[20:23], v52 offset0:24 offset1:28
	s_waitcnt lgkmcnt(0)
	v_mfma_f32_16x16x32_bf16 v[4:7], v[20:23], v[16:19], v[4:7]
	ds_read2_b64 v[20:23], v53 offset0:56 offset1:60
	s_waitcnt lgkmcnt(0)
	v_mfma_f32_16x16x32_bf16 v[8:11], v[20:23], v[16:19], v[8:11]
	ds_read2_b64 v[20:23], v54 offset0:88 offset1:92
	s_waitcnt lgkmcnt(0)
	v_mfma_f32_16x16x32_bf16 v[12:15], v[20:23], v[16:19], v[12:15]
	ds_read2_b64 v[20:23], v55 offset0:24 offset1:28
	s_waitcnt lgkmcnt(0)
	v_mfma_f32_16x16x32_bf16 v[0:3], v[20:23], v[16:19], v[0:3]
	v_cvt_pk_bf16_f32 v16, v32, v33
	v_cvt_pk_bf16_f32 v17, v34, v35
	v_cvt_pk_bf16_f32 v18, v28, v29
	v_cvt_pk_bf16_f32 v19, v30, v31
	ds_read2_b64 v[20:23], v52 offset0:32 offset1:36
	s_waitcnt lgkmcnt(0)
	v_mfma_f32_16x16x32_bf16 v[4:7], v[20:23], v[16:19], v[4:7]
	ds_read2_b64 v[20:23], v53 offset0:64 offset1:68
	s_waitcnt lgkmcnt(0)
	v_mfma_f32_16x16x32_bf16 v[8:11], v[20:23], v[16:19], v[8:11]
	ds_read2_b64 v[20:23], v54 offset0:96 offset1:100
	s_waitcnt lgkmcnt(0)
	v_mfma_f32_16x16x32_bf16 v[12:15], v[20:23], v[16:19], v[12:15]
	ds_read2_b64 v[20:23], v55 offset0:32 offset1:36
	s_waitcnt lgkmcnt(0)
	v_mfma_f32_16x16x32_bf16 v[0:3], v[20:23], v[16:19], v[0:3]
	v_cvt_pk_bf16_f32 v16, v24, v25
	v_cvt_pk_bf16_f32 v17, v26, v27
	v_cvt_pk_bf16_f32 v18, v106, v107
	v_cvt_pk_bf16_f32 v19, v108, v109
	ds_read2_b64 v[20:23], v52 offset0:40 offset1:44
	s_waitcnt lgkmcnt(0)
	v_mfma_f32_16x16x32_bf16 v[4:7], v[20:23], v[16:19], v[4:7]
	ds_read2_b64 v[20:23], v53 offset0:72 offset1:76
	s_waitcnt lgkmcnt(0)
	v_mfma_f32_16x16x32_bf16 v[8:11], v[20:23], v[16:19], v[8:11]
	ds_read2_b64 v[20:23], v54 offset0:104 offset1:108
	s_waitcnt lgkmcnt(0)
	v_mfma_f32_16x16x32_bf16 v[12:15], v[20:23], v[16:19], v[12:15]
	ds_read2_b64 v[20:23], v55 offset0:40 offset1:44
	s_waitcnt lgkmcnt(0)
	v_mfma_f32_16x16x32_bf16 v[0:3], v[20:23], v[16:19], v[0:3]
	v_cvt_pk_bf16_f32 v16, v110, v111
	v_cvt_pk_bf16_f32 v17, v112, v113
	v_cvt_pk_bf16_f32 v18, v114, v115
	v_cvt_pk_bf16_f32 v19, v116, v117
	ds_read2_b64 v[20:23], v52 offset0:48 offset1:52
	s_waitcnt lgkmcnt(0)
	v_mfma_f32_16x16x32_bf16 v[4:7], v[20:23], v[16:19], v[4:7]
	ds_read2_b64 v[20:23], v53 offset0:80 offset1:84
	s_waitcnt lgkmcnt(0)
	v_mfma_f32_16x16x32_bf16 v[8:11], v[20:23], v[16:19], v[8:11]
	ds_read2_b64 v[20:23], v54 offset0:112 offset1:116
	s_waitcnt lgkmcnt(0)
	v_mfma_f32_16x16x32_bf16 v[12:15], v[20:23], v[16:19], v[12:15]
	ds_read2_b64 v[20:23], v55 offset0:48 offset1:52
	s_waitcnt lgkmcnt(0)
	v_mfma_f32_16x16x32_bf16 v[0:3], v[20:23], v[16:19], v[0:3]
	v_cvt_pk_bf16_f32 v16, v118, v119
	v_cvt_pk_bf16_f32 v17, v120, v121
	v_cvt_pk_bf16_f32 v18, v122, v123
	v_cvt_pk_bf16_f32 v19, v124, v125
	ds_read2_b64 v[20:23], v52 offset0:56 offset1:60
	s_waitcnt lgkmcnt(0)
	v_mfma_f32_16x16x32_bf16 v[4:7], v[20:23], v[16:19], v[4:7]
	ds_read2_b64 v[20:23], v53 offset0:88 offset1:92
	s_waitcnt lgkmcnt(0)
	v_mfma_f32_16x16x32_bf16 v[8:11], v[20:23], v[16:19], v[8:11]
	ds_read2_b64 v[20:23], v54 offset0:120 offset1:124
	s_waitcnt lgkmcnt(0)
	v_mfma_f32_16x16x32_bf16 v[12:15], v[20:23], v[16:19], v[12:15]
	ds_read2_b64 v[20:23], v55 offset0:56 offset1:60
	s_waitcnt lgkmcnt(0)
	v_mfma_f32_16x16x32_bf16 v[0:3], v[20:23], v[16:19], v[0:3]
	v_add_f32_e32 v16, v126, v127
	v_div_scale_f32 v17, s[8:9], v16, v16, 1.0
	v_rcp_f32_e32 v18, v17
	s_nop 0
	v_fma_f32 v19, -v17, v18, 1.0
	v_fmac_f32_e32 v18, v19, v18
	v_div_scale_f32 v19, vcc, 1.0, v16, 1.0
	v_mul_f32_e32 v20, v19, v18
	v_fma_f32 v21, -v17, v20, v19
	v_fmac_f32_e32 v20, v21, v18
	v_fma_f32 v17, -v17, v20, v19
	v_div_fmas_f32 v17, v17, v18, v20
	v_div_fixup_f32 v18, v17, v16, 1.0
	v_lshlrev_b64 v[16:17], 11, v[68:69]
	v_lshl_add_u64 v[16:17], s[66:67], 0, v[16:17]
	v_mul_f32_e32 v4, v18, v4
	v_mul_f32_e32 v5, v18, v5
	v_lshl_add_u64 v[16:17], v[16:17], 0, s[70:71]
	v_cvt_pk_bf16_f32 v4, v4, v5
	v_mul_f32_e32 v5, v18, v6
	v_lshl_add_u64 v[16:17], v[16:17], 0, v[184:185]
	v_mul_f32_e32 v6, v18, v7
	v_cvt_pk_bf16_f32 v5, v5, v6
	global_store_dwordx2 v[16:17], v[4:5], off offset:1536
	v_mul_f32_e32 v4, v18, v8
	v_mul_f32_e32 v5, v18, v9
	v_cvt_pk_bf16_f32 v4, v4, v5
	v_mul_f32_e32 v5, v18, v10
	v_mul_f32_e32 v6, v18, v11
	v_cvt_pk_bf16_f32 v5, v5, v6
	global_store_dwordx2 v[16:17], v[4:5], off offset:1568
	v_mul_f32_e32 v4, v18, v12
	v_mul_f32_e32 v5, v18, v13
	v_cvt_pk_bf16_f32 v4, v4, v5
	v_mul_f32_e32 v5, v18, v14
	v_mul_f32_e32 v0, v18, v0
	v_mul_f32_e32 v1, v18, v1
	v_mul_f32_e32 v6, v18, v15
	v_cvt_pk_bf16_f32 v5, v5, v6
	global_store_dwordx2 v[16:17], v[4:5], off offset:1600
	v_cvt_pk_bf16_f32 v0, v0, v1
	v_mul_f32_e32 v1, v18, v2
	v_mul_f32_e32 v2, v18, v3
	v_cvt_pk_bf16_f32 v1, v1, v2
	global_store_dwordx2 v[16:17], v[0:1], off offset:1632
	s_barrier
	s_cbranch_scc0 .LBB0_269
.LBB0_270:
	v_readlane_b32 s6, v252, 33
	s_mov_b64 s[8:9], -1
	v_add_u32_e32 v25, s6, v76
	s_mov_b32 s98, s76
	s_mov_b32 s99, s22
	s_mov_b32 s101, 0x7fffffff
	s_cmp_eq_u32 s100, 1
	s_cbranch_scc0 .Lmix_nomap
	v_readlane_b32 s6, v252, 0
	s_nop 0
	s_and_b32 s13, s6, 7
	s_lshr_b32 s6, s6, 3
	s_lshl_b32 s6, s6, 9
	s_movk_i32 s98, 0x4000
	s_cmp_eq_u64 s[0:1], 0
	s_cbranch_scc0 .Lmix_pool
	s_mul_i32 s14, s13, 0x60000
	s_add_i32 s6, s6, s14
	s_add_i32 s99, s14, 0x5ffff
	s_branch .Lmix_set
.Lmix_pool:
	s_mul_i32 s14, s13, 0x18000
	s_add_i32 s6, s6, s14
	s_add_i32 s99, s14, 0x257fff
	s_mov_b32 s101, 6
.Lmix_set:
	v_add_u32_e32 v25, s6, v76
.Lmix_nomap:
	s_and_b64 vcc, exec, s[0:1]
	s_mov_b32 s6, 0x300000
	v_cmp_gt_i32_e64 s[36:37], s6, v25
	s_cbranch_vccz .LBB0_287
	s_and_saveexec_b64 s[8:9], s[36:37]
	s_cbranch_execz .LBB0_286
	s_mov_b64 s[10:11], 0
	v_mov_b32_e32 v24, v25
	s_branch .LBB0_274
.LBB0_273:
	v_lshlrev_b64 v[4:5], 10, v[26:27]
	s_sub_i32 s101, s101, 1
	s_cmp_eq_u32 s101, 0
	s_cselect_b32 vcc_lo, 0xac000, s98
	s_cselect_b32 s101, 6, s101
	s_nop 0
	v_add_u32_e32 v24, vcc_lo, v24
	v_lshl_add_u64 v[4:5], v[4:5], 1, s[66:67]
	v_cmp_lt_i32_e32 vcc, s99, v24
	v_lshl_add_u64 v[4:5], v[28:29], 1, v[4:5]
	s_or_b64 s[10:11], vcc, s[10:11]
	global_store_dwordx4 v[4:5], v[0:3], off
	s_andn2_b64 exec, exec, s[10:11]
	s_cbranch_execz .LBB0_286

.LBB0_287:
	s_andn2_b64 vcc, exec, s[8:9]
	s_cbranch_vccnz .LBB0_292
	s_and_saveexec_b64 s[8:9], s[36:37]
	v_readlane_b32 s36, v252, 17
	v_readlane_b32 s40, v252, 21
	v_readlane_b32 s41, v252, 22
	v_readlane_b32 s37, v252, 18
	v_readlane_b32 s38, v252, 19
	v_readlane_b32 s39, v252, 20
	v_readlane_b32 s42, v252, 23
	v_readlane_b32 s43, v252, 24
	v_readlane_b32 s44, v252, 25
	v_readlane_b32 s45, v252, 26
	v_readlane_b32 s46, v252, 27
	v_readlane_b32 s47, v252, 28
	v_readlane_b32 s48, v252, 29
	v_readlane_b32 s49, v252, 30
	v_readlane_b32 s50, v252, 31
	v_readlane_b32 s51, v252, 32
	s_cbranch_execz .LBB0_291
	s_mov_b64 s[12:13], s[40:41]
	v_lshlrev_b32_e32 v0, 3, v25
	s_lshl_b32 s6, s98, 3
	s_mov_b64 s[10:11], 0
.LBB0_290:
	v_mul_hi_i32 v1, v25, s84
	v_lshrrev_b32_e32 v4, 31, v1
	v_ashrrev_i32_e32 v1, 4, v1
	v_mov_b64_e32 v[2:3], s[72:73]
	v_add_u32_e32 v4, v1, v4
	v_mad_i64_i32 v[2:3], s[0:1], v4, s85, v[2:3]
	v_add_u32_e32 v25, s98, v25
	v_and_b32_e32 v1, 0x1fff, v4
	s_movk_i32 s0, 0xfd00
	v_cmp_lt_i32_e32 vcc, s99, v25
	v_mad_u64_u32 v[6:7], s[0:1], v4, s0, v[0:1]
	s_or_b64 s[10:11], vcc, s[10:11]
	v_cmp_gt_u32_e32 vcc, 2, v1
	v_cmp_eq_u32_e64 s[0:1], 0, v1
	v_mov_b32_e32 v1, 0xffffe400
	v_ashrrev_i32_e32 v7, 31, v6
	v_cndmask_b32_e64 v22, v1, 0, vcc
	v_mov_b32_e32 v1, 0xfffff200
	v_cndmask_b32_e64 v39, -1, 0, s[0:1]
	v_lshl_add_u64 v[20:21], v[6:7], 2, s[12:13]
	v_cndmask_b32_e64 v38, v1, 0, s[0:1]
	v_cndmask_b32_e64 v46, 1.0, 0, s[0:1]
	s_mov_b64 s[0:1], 0x1800
	v_ashrrev_i32_e32 v5, 31, v4
	v_lshlrev_b64 v[18:19], 1, v[6:7]
	v_lshl_add_u64 v[34:35], v[20:21], 0, s[0:1]
	s_movk_i32 s0, 0x1000
	v_cndmask_b32_e64 v23, -1, 0, vcc
	v_lshlrev_b64 v[4:5], 11, v[4:5]
	v_cndmask_b32_e64 v24, 1.0, 0, vcc
	v_lshl_add_u64 v[40:41], v[2:3], 0, v[18:19]
	v_add_co_u32_e32 v30, vcc, s0, v20
	v_lshl_add_u64 v[26:27], s[66:67], 0, v[4:5]
	global_load_dwordx4 v[2:5], v[20:21], off offset:16
	global_load_dwordx4 v[6:9], v[20:21], off
	global_load_dwordx4 v[10:13], v[20:21], off offset:3088
	global_load_dwordx4 v[14:17], v[20:21], off offset:3072
	v_addc_co_u32_e32 v31, vcc, 0, v21, vcc
	v_lshl_add_u64 v[22:23], v[40:41], 0, v[22:23]
	v_lshl_add_u64 v[42:43], v[40:41], 0, v[38:39]
	v_lshl_add_u64 v[48:49], v[26:27], 0, v[18:19]
	global_load_dwordx4 v[18:21], v[40:41], off
	global_load_dwordx4 v[26:29], v[40:41], off offset:1536
	s_nop 0
	global_load_dwordx4 v[30:33], v[30:31], off offset:2048
	s_nop 0
	global_load_dwordx4 v[34:37], v[34:35], off offset:16
	s_nop 0
	global_load_dwordx4 v[38:41], v[22:23], off offset:1536
	s_nop 0
	global_load_dwordx4 v[42:45], v[42:43], off offset:1536
	v_add_u32_e32 v0, s6, v0
	s_waitcnt vmcnt(0)
	v_pk_mul_f32 v[4:5], v[4:5], v[24:25] op_sel_hi:[1,0]
	v_pk_mul_f32 v[8:9], v[8:9], v[24:25] op_sel_hi:[1,0]
	v_pk_mul_f32 v[12:13], v[46:47], v[12:13] op_sel_hi:[0,1]
	v_pk_mul_f32 v[16:17], v[46:47], v[16:17] op_sel_hi:[0,1]
	v_pk_mul_f32 v[14:15], v[46:47], v[14:15] op_sel_hi:[0,1]
	v_pk_mul_f32 v[10:11], v[46:47], v[10:11] op_sel_hi:[0,1]
	v_pk_mul_f32 v[6:7], v[6:7], v[24:25] op_sel_hi:[1,0]
	v_pk_mul_f32 v[2:3], v[2:3], v[24:25] op_sel_hi:[1,0]
	v_lshlrev_b32_e32 v1, 16, v18
	v_and_b32_e32 v24, 0xffff0000, v18
	v_lshlrev_b32_e32 v56, 16, v19
	v_and_b32_e32 v57, 0xffff0000, v19
	v_lshlrev_b32_e32 v58, 16, v20
	v_and_b32_e32 v59, 0xffff0000, v20
	v_lshlrev_b32_e32 v60, 16, v21
	v_and_b32_e32 v61, 0xffff0000, v21
	v_lshlrev_b32_e32 v19, 16, v26
	v_mov_b32_e32 v20, v14
	v_mov_b32_e32 v21, v30
	v_and_b32_e32 v23, 0xffff0000, v26
	v_mov_b32_e32 v30, v15
	v_lshlrev_b32_e32 v15, 16, v27
	v_mov_b32_e32 v46, v16
	v_mov_b32_e32 v47, v32
	v_and_b32_e32 v27, 0xffff0000, v27
	v_mov_b32_e32 v32, v17
	v_lshlrev_b32_e32 v17, 16, v28
	v_mov_b32_e32 v50, v10
	v_mov_b32_e32 v51, v34
	v_mov_b32_e32 v54, v12
	v_mov_b32_e32 v55, v36
	v_mov_b32_e32 v36, v13
	v_lshlrev_b32_e32 v12, 16, v38
	v_and_b32_e32 v13, 0xffff0000, v38
	v_lshlrev_b32_e32 v38, 16, v39
	v_and_b32_e32 v39, 0xffff0000, v39
	v_lshlrev_b32_e32 v62, 16, v40
	v_and_b32_e32 v40, 0xffff0000, v40
	v_lshlrev_b32_e32 v63, 16, v41
	v_and_b32_e32 v41, 0xffff0000, v41
	v_lshlrev_b32_e32 v18, 16, v42
	v_and_b32_e32 v22, 0xffff0000, v42
	v_lshlrev_b32_e32 v14, 16, v43
	v_and_b32_e32 v26, 0xffff0000, v43
	v_lshlrev_b32_e32 v16, 16, v44
	v_and_b32_e32 v53, 0xffff0000, v28
	v_mov_b32_e32 v34, v11
	v_lshlrev_b32_e32 v11, 16, v29
	v_and_b32_e32 v29, 0xffff0000, v29
	v_and_b32_e32 v52, 0xffff0000, v44
	v_lshlrev_b32_e32 v10, 16, v45
	v_and_b32_e32 v28, 0xffff0000, v45
	v_fma_f32 v42, v6, v12, 0
	v_fma_f32 v43, v7, v13, 0
	v_fma_f32 v38, v8, v38, 0
	v_fma_f32 v39, v9, v39, 0
	v_fma_f32 v44, v2, v62, 0
	v_fma_f32 v40, v3, v40, 0
	v_fma_f32 v45, v4, v63, 0
	v_fma_f32 v41, v5, v41, 0
	v_pk_mul_f32 v[2:3], v[20:21], v[18:19]
	v_pk_mul_f32 v[4:5], v[30:31], v[22:23]
	v_pk_mul_f32 v[6:7], v[46:47], v[14:15]
	v_pk_mul_f32 v[8:9], v[32:33], v[26:27]
	v_pk_mul_f32 v[12:13], v[50:51], v[16:17]
	v_pk_mul_f32 v[14:15], v[34:35], v[52:53]
	v_pk_mul_f32 v[10:11], v[54:55], v[10:11]
	v_pk_mul_f32 v[16:17], v[36:37], v[28:29]
	v_add_f32_e32 v2, v2, v42
	v_add_f32_e32 v4, v4, v43
	v_add_f32_e32 v6, v6, v38
	v_add_f32_e32 v8, v8, v39
	v_add_f32_e32 v12, v44, v12
	v_add_f32_e32 v14, v40, v14
	v_add_f32_e32 v10, v45, v10
	v_add_f32_e32 v16, v41, v16
	v_add_f32_e32 v2, v2, v3
	v_add_f32_e32 v3, v4, v5
	v_add_f32_e32 v4, v6, v7
	v_add_f32_e32 v5, v8, v9
	v_add_f32_e32 v6, v12, v13
	v_add_f32_e32 v7, v14, v15
	v_add_f32_e32 v8, v10, v11
	v_add_f32_e32 v9, v16, v17
	v_mul_f32_e32 v1, v2, v1
	v_mul_f32_e32 v2, v3, v24
	v_mul_f32_e32 v3, v4, v56
	v_mul_f32_e32 v4, v5, v57
	v_mul_f32_e32 v5, v6, v58
	v_mul_f32_e32 v6, v7, v59
	v_mul_f32_e32 v7, v8, v60
	v_mul_f32_e32 v8, v9, v61
	v_cvt_pk_bf16_f32 v2, v1, v2
	v_cvt_pk_bf16_f32 v3, v3, v4
	v_cvt_pk_bf16_f32 v4, v5, v6
	v_cvt_pk_bf16_f32 v5, v7, v8
	global_store_dwordx4 v[48:49], v[2:5], off
	s_andn2_b64 exec, exec, s[10:11]
	s_cbranch_execnz .LBB0_290

.LBB0_515:
	s_waitcnt vmcnt(0)
	s_waitcnt vmcnt(0) lgkmcnt(0)
	s_barrier
	s_and_saveexec_b64 s[0:1], s[62:63]
	s_cbranch_execz .LBB0_202
	v_readlane_b32 s6, v254, 49
	s_mov_b32 s9, 0x3dfb
	s_nop 0
	s_lshr_b32 s12, s9, s6
	s_and_b32 s12, s12, s100
	s_and_b32 s12, s12, 1
	s_cmp_eq_u32 s12, 0
	s_cbranch_scc1 .Lgbar
	s_lshl_b32 s12, 2, s6
	s_sub_i32 s12, s12, 1
	s_and_b32 s12, s12, s9
	s_bcnt1_i32_b32 s12, s12
	s_lshl_b32 s9, s12, 5
	v_readlane_b32 s8, v252, 0
	v_readlane_b32 s10, v252, 45
	v_readlane_b32 s11, v252, 46
	s_and_b32 s8, s8, 7
	s_mov_b32 s16, 0x0e060301
	s_mov_b32 s17, 0xb058281c
	s_cmp_eq_u32 s6, 1
	s_cbranch_scc1 .Llb_tab
	s_mov_b32 s16, 0x0a060301
	s_mov_b32 s17, 0x88482414
	s_cmp_eq_u32 s6, 6
	s_cbranch_scc1 .Llb_tab
	s_mov_b32 s16, 0x0c060301
	s_mov_b32 s17, 0xa070381c
	s_cmp_eq_u32 s6, 8
	s_cbranch_scc1 .Llb_tab
	s_mov_b32 s16, 0xf83c1e07
	s_mov_b32 s17, 0x8040a0d0
	s_cmp_eq_u32 s6, 4
	s_cbranch_scc1 .Llb_tab
	s_mov_b32 s16, 0x783c0e07
	s_mov_b32 s17, 0x8040e0f0
	s_cmp_eq_u32 s6, 11
	s_cbranch_scc1 .Llb_tab
	s_lshl_b32 s13, 1, s8
	s_branch .Llb_have
